# remove redundant s_setprio 0/1 pairs between MMA halves in all GEMM K-loops
# speedup vs baseline: 1.0020x; 1.0020x over previous
.LBB0_39:
	s_add_u32 s58, s56, 0xfffc0080
	s_addc_u32 s59, s57, -1
	s_add_i32 s77, 0, 0x10000
	s_cmp_eq_u32 s76, 12
	s_cselect_b32 s61, s4, s59
	s_cselect_b32 s60, s5, s58
	s_cselect_b32 s59, s41, s75
	s_cselect_b32 s58, s49, s51
	s_add_i32 s80, 0, 0x14000
	v_add_u32_e32 v68, s77, v250
	v_add_u32_e32 v166, s80, v250
	ds_read_b128 v[40:43], v68
	ds_read_b128 v[48:51], v68 offset:1024
	ds_read_b128 v[60:63], v68 offset:2048
	ds_read_b128 v[68:71], v68 offset:3072
	ds_read_b128 v[146:149], v166
	ds_read_b128 v[150:153], v166 offset:1024
	ds_read_b128 v[154:157], v166 offset:2048
	ds_read_b128 v[166:169], v166 offset:3072
	v_lshl_add_u64 v[202:203], s[56:57], 0, v[162:163]
	s_add_i32 m0, s30, 0xc000
	ds_read_b128 v[170:173], v251
	ds_read_b128 v[174:177], v251 offset:1024
	ds_read_b128 v[178:181], v251 offset:2048
	ds_read_b128 v[182:185], v251 offset:3072
	ds_read_b128 v[186:189], v251 offset:4096
	ds_read_b128 v[190:193], v251 offset:5120
	ds_read_b128 v[194:197], v251 offset:6144
	ds_read_b128 v[198:201], v251 offset:7168
	global_load_lds_dwordx4 v[202:203], off
	v_lshl_add_u64 v[202:203], s[56:57], 0, v[164:165]
	s_add_i32 m0, s30, 0xe000
	s_nop 0
	global_load_lds_dwordx4 v[202:203], off
	s_waitcnt vmcnt(8)
	s_waitcnt lgkmcnt(0)
	s_barrier
	s_setprio 1
	s_waitcnt lgkmcnt(0)
	v_mfma_f32_16x16x32_bf16 v[140:143], v[40:43], v[170:173], v[140:143]
	v_mfma_f32_16x16x32_bf16 v[136:139], v[60:63], v[170:173], v[136:139]
	v_mfma_f32_16x16x32_bf16 v[124:127], v[40:43], v[178:181], v[124:127]
	v_mfma_f32_16x16x32_bf16 v[120:123], v[60:63], v[178:181], v[120:123]
	v_mfma_f32_16x16x32_bf16 v[108:111], v[40:43], v[186:189], v[108:111]
	v_mfma_f32_16x16x32_bf16 v[104:107], v[60:63], v[186:189], v[104:107]
	v_mfma_f32_16x16x32_bf16 v[92:95], v[40:43], v[194:197], v[92:95]
	v_mfma_f32_16x16x32_bf16 v[88:91], v[60:63], v[194:197], v[88:91]
	v_mfma_f32_16x16x32_bf16 v[140:143], v[48:51], v[174:177], v[140:143]
	v_mfma_f32_16x16x32_bf16 v[136:139], v[68:71], v[174:177], v[136:139]
	v_mfma_f32_16x16x32_bf16 v[124:127], v[48:51], v[182:185], v[124:127]
	v_mfma_f32_16x16x32_bf16 v[120:123], v[68:71], v[182:185], v[120:123]
	v_mfma_f32_16x16x32_bf16 v[108:111], v[48:51], v[190:193], v[108:111]
	v_mfma_f32_16x16x32_bf16 v[104:107], v[68:71], v[190:193], v[104:107]
	v_mfma_f32_16x16x32_bf16 v[92:95], v[48:51], v[198:201], v[92:95]
	v_mfma_f32_16x16x32_bf16 v[88:91], v[68:71], v[198:201], v[88:91]
	v_mfma_f32_16x16x32_bf16 v[132:135], v[146:149], v[170:173], v[132:135]
	v_mfma_f32_16x16x32_bf16 v[128:131], v[154:157], v[170:173], v[128:131]
	v_mfma_f32_16x16x32_bf16 v[116:119], v[146:149], v[178:181], v[116:119]
	v_mfma_f32_16x16x32_bf16 v[112:115], v[154:157], v[178:181], v[112:115]
	v_mfma_f32_16x16x32_bf16 v[100:103], v[146:149], v[186:189], v[100:103]
	v_mfma_f32_16x16x32_bf16 v[96:99], v[154:157], v[186:189], v[96:99]
	v_mfma_f32_16x16x32_bf16 v[84:87], v[146:149], v[194:197], v[84:87]
	v_mfma_f32_16x16x32_bf16 v[80:83], v[154:157], v[194:197], v[80:83]
	v_mfma_f32_16x16x32_bf16 v[132:135], v[150:153], v[174:177], v[132:135]
	v_mfma_f32_16x16x32_bf16 v[128:131], v[166:169], v[174:177], v[128:131]
	v_mfma_f32_16x16x32_bf16 v[116:119], v[150:153], v[182:185], v[116:119]
	v_mfma_f32_16x16x32_bf16 v[112:115], v[166:169], v[182:185], v[112:115]
	v_mfma_f32_16x16x32_bf16 v[100:103], v[150:153], v[190:193], v[100:103]
	v_mfma_f32_16x16x32_bf16 v[96:99], v[166:169], v[190:193], v[96:99]
	v_mfma_f32_16x16x32_bf16 v[84:87], v[150:153], v[198:201], v[84:87]
	v_mfma_f32_16x16x32_bf16 v[80:83], v[166:169], v[198:201], v[80:83]
	s_setprio 0
	s_barrier
	s_add_i32 s77, s77, s27
	v_lshl_add_u64 v[202:203], s[58:59], 0, v[144:145]
	s_mov_b32 m0, s77
	ds_read_b128 v[170:173], v251 offset:16384
	ds_read_b128 v[174:177], v251 offset:17408
	ds_read_b128 v[178:181], v251 offset:18432
	ds_read_b128 v[182:185], v251 offset:19456
	ds_read_b128 v[186:189], v251 offset:20480
	ds_read_b128 v[190:193], v251 offset:21504
	ds_read_b128 v[194:197], v251 offset:22528
	ds_read_b128 v[198:201], v251 offset:23552
	global_load_lds_dwordx4 v[202:203], off
	s_add_i32 m0, s77, 0x2000
	s_add_u32 s78, s58, 0x40000
	v_lshl_add_u64 v[204:205], s[58:59], 0, v[160:161]
	s_addc_u32 s79, s59, 0
	s_add_i32 s77, s80, s27
	global_load_lds_dwordx4 v[204:205], off
	v_lshl_add_u64 v[206:207], s[78:79], 0, v[144:145]
	s_mov_b32 m0, s77
	v_lshl_add_u64 v[208:209], s[60:61], 0, v[160:161]
	global_load_lds_dwordx4 v[206:207], off
	v_lshl_add_u64 v[206:207], s[78:79], 0, v[160:161]
	s_add_i32 m0, s77, 0x2000
	s_nop 0
	global_load_lds_dwordx4 v[206:207], off
	v_lshl_add_u64 v[206:207], s[60:61], 0, v[144:145]
	s_mov_b32 m0, s30
	s_nop 0
	global_load_lds_dwordx4 v[206:207], off
	s_mov_b32 m0, s62
	s_nop 0
	global_load_lds_dwordx4 v[208:209], off
	s_waitcnt vmcnt(8)
	s_waitcnt lgkmcnt(0)
	s_barrier
	s_setprio 1
	s_waitcnt lgkmcnt(0)
	v_mfma_f32_16x16x32_bf16 v[76:79], v[40:43], v[170:173], v[76:79]
	v_mfma_f32_16x16x32_bf16 v[72:75], v[60:63], v[170:173], v[72:75]
	v_mfma_f32_16x16x32_bf16 v[52:55], v[40:43], v[178:181], v[52:55]
	v_mfma_f32_16x16x32_bf16 v[44:47], v[60:63], v[178:181], v[44:47]
	v_mfma_f32_16x16x32_bf16 v[28:31], v[40:43], v[186:189], v[28:31]
	v_mfma_f32_16x16x32_bf16 v[24:27], v[60:63], v[186:189], v[24:27]
	v_mfma_f32_16x16x32_bf16 v[12:15], v[40:43], v[194:197], v[12:15]
	v_mfma_f32_16x16x32_bf16 v[8:11], v[60:63], v[194:197], v[8:11]
	v_mfma_f32_16x16x32_bf16 v[76:79], v[48:51], v[174:177], v[76:79]
	v_mfma_f32_16x16x32_bf16 v[72:75], v[68:71], v[174:177], v[72:75]
	v_mfma_f32_16x16x32_bf16 v[52:55], v[48:51], v[182:185], v[52:55]
	v_mfma_f32_16x16x32_bf16 v[44:47], v[68:71], v[182:185], v[44:47]
	v_mfma_f32_16x16x32_bf16 v[28:31], v[48:51], v[190:193], v[28:31]
	v_mfma_f32_16x16x32_bf16 v[24:27], v[68:71], v[190:193], v[24:27]
	v_mfma_f32_16x16x32_bf16 v[12:15], v[48:51], v[198:201], v[12:15]
	v_mfma_f32_16x16x32_bf16 v[8:11], v[68:71], v[198:201], v[8:11]
	v_mfma_f32_16x16x32_bf16 v[36:39], v[146:149], v[178:181], v[36:39]
	v_mfma_f32_16x16x32_bf16 v[32:35], v[154:157], v[178:181], v[32:35]
	v_mfma_f32_16x16x32_bf16 v[20:23], v[146:149], v[186:189], v[20:23]
	v_mfma_f32_16x16x32_bf16 v[16:19], v[154:157], v[186:189], v[16:19]
	v_mfma_f32_16x16x32_bf16 v[4:7], v[146:149], v[194:197], v[4:7]
	v_mfma_f32_16x16x32_bf16 v[0:3], v[154:157], v[194:197], v[0:3]
	v_mfma_f32_16x16x32_bf16 v[40:43], v[146:149], v[170:173], v[64:67]
	v_mfma_f32_16x16x32_bf16 v[48:51], v[154:157], v[170:173], v[56:59]
	v_mfma_f32_16x16x32_bf16 v[36:39], v[150:153], v[182:185], v[36:39]
	v_mfma_f32_16x16x32_bf16 v[32:35], v[166:169], v[182:185], v[32:35]
	v_mfma_f32_16x16x32_bf16 v[20:23], v[150:153], v[190:193], v[20:23]
	v_mfma_f32_16x16x32_bf16 v[16:19], v[166:169], v[190:193], v[16:19]
	v_mfma_f32_16x16x32_bf16 v[4:7], v[150:153], v[198:201], v[4:7]
	v_mfma_f32_16x16x32_bf16 v[0:3], v[166:169], v[198:201], v[0:3]
	v_mfma_f32_16x16x32_bf16 v[40:43], v[150:153], v[174:177], v[40:43]
	v_mfma_f32_16x16x32_bf16 v[48:51], v[166:169], v[174:177], v[48:51]
	s_setprio 0
	s_barrier
	s_add_i32 s77, 0, 0x18000
	s_add_i32 s78, 0, 0x1c000
	v_add_u32_e32 v68, s77, v250
	v_add_u32_e32 v166, s78, v250
	ds_read_b128 v[56:59], v68
	ds_read_b128 v[60:63], v68 offset:1024
	ds_read_b128 v[64:67], v68 offset:2048
	ds_read_b128 v[68:71], v68 offset:3072
	ds_read_b128 v[146:149], v166
	ds_read_b128 v[150:153], v166 offset:1024
	ds_read_b128 v[154:157], v166 offset:2048
	ds_read_b128 v[166:169], v166 offset:3072
	s_add_u32 s60, s60, 0x40000
	s_addc_u32 s61, s61, 0
	s_mov_b32 m0, s63
	v_lshl_add_u64 v[210:211], s[60:61], 0, v[144:145]
	ds_read_b128 v[170:173], v251 offset:32768
	ds_read_b128 v[174:177], v251 offset:33792
	ds_read_b128 v[178:181], v251 offset:34816
	ds_read_b128 v[182:185], v251 offset:35840
	ds_read_b128 v[186:189], v251 offset:36864
	ds_read_b128 v[190:193], v251 offset:37888
	ds_read_b128 v[194:197], v251 offset:38912
	ds_read_b128 v[198:201], v251 offset:39936
	global_load_lds_dwordx4 v[210:211], off
	v_lshl_add_u64 v[210:211], s[60:61], 0, v[160:161]
	s_mov_b32 m0, s64
	s_nop 0
	global_load_lds_dwordx4 v[210:211], off
	s_waitcnt vmcnt(8)
	s_waitcnt lgkmcnt(0)
	s_barrier
	s_setprio 1
	s_waitcnt lgkmcnt(0)
	v_mfma_f32_16x16x32_bf16 v[140:143], v[56:59], v[170:173], v[140:143]
	v_mfma_f32_16x16x32_bf16 v[136:139], v[64:67], v[170:173], v[136:139]
	v_mfma_f32_16x16x32_bf16 v[124:127], v[56:59], v[178:181], v[124:127]
	v_mfma_f32_16x16x32_bf16 v[120:123], v[64:67], v[178:181], v[120:123]
	v_mfma_f32_16x16x32_bf16 v[108:111], v[56:59], v[186:189], v[108:111]
	v_mfma_f32_16x16x32_bf16 v[104:107], v[64:67], v[186:189], v[104:107]
	v_mfma_f32_16x16x32_bf16 v[92:95], v[56:59], v[194:197], v[92:95]
	v_mfma_f32_16x16x32_bf16 v[88:91], v[64:67], v[194:197], v[88:91]
	v_mfma_f32_16x16x32_bf16 v[140:143], v[60:63], v[174:177], v[140:143]
	v_mfma_f32_16x16x32_bf16 v[136:139], v[68:71], v[174:177], v[136:139]
	v_mfma_f32_16x16x32_bf16 v[124:127], v[60:63], v[182:185], v[124:127]
	v_mfma_f32_16x16x32_bf16 v[120:123], v[68:71], v[182:185], v[120:123]
	v_mfma_f32_16x16x32_bf16 v[108:111], v[60:63], v[190:193], v[108:111]
	v_mfma_f32_16x16x32_bf16 v[104:107], v[68:71], v[190:193], v[104:107]
	v_mfma_f32_16x16x32_bf16 v[92:95], v[60:63], v[198:201], v[92:95]
	v_mfma_f32_16x16x32_bf16 v[88:91], v[68:71], v[198:201], v[88:91]
	v_mfma_f32_16x16x32_bf16 v[132:135], v[146:149], v[170:173], v[132:135]
	v_mfma_f32_16x16x32_bf16 v[128:131], v[154:157], v[170:173], v[128:131]
	v_mfma_f32_16x16x32_bf16 v[116:119], v[146:149], v[178:181], v[116:119]
	v_mfma_f32_16x16x32_bf16 v[112:115], v[154:157], v[178:181], v[112:115]
	v_mfma_f32_16x16x32_bf16 v[100:103], v[146:149], v[186:189], v[100:103]
	v_mfma_f32_16x16x32_bf16 v[96:99], v[154:157], v[186:189], v[96:99]
	v_mfma_f32_16x16x32_bf16 v[84:87], v[146:149], v[194:197], v[84:87]
	v_mfma_f32_16x16x32_bf16 v[80:83], v[154:157], v[194:197], v[80:83]
	v_mfma_f32_16x16x32_bf16 v[132:135], v[150:153], v[174:177], v[132:135]
	v_mfma_f32_16x16x32_bf16 v[128:131], v[166:169], v[174:177], v[128:131]
	v_mfma_f32_16x16x32_bf16 v[116:119], v[150:153], v[182:185], v[116:119]
	v_mfma_f32_16x16x32_bf16 v[112:115], v[166:169], v[182:185], v[112:115]
	v_mfma_f32_16x16x32_bf16 v[100:103], v[150:153], v[190:193], v[100:103]
	v_mfma_f32_16x16x32_bf16 v[96:99], v[166:169], v[190:193], v[96:99]
	v_mfma_f32_16x16x32_bf16 v[84:87], v[150:153], v[198:201], v[84:87]
	v_mfma_f32_16x16x32_bf16 v[80:83], v[166:169], v[198:201], v[80:83]
	s_setprio 0
	s_barrier
	s_add_i32 s60, s77, s27
	v_lshl_add_u64 v[202:203], v[202:203], 0, s[20:21]
	s_mov_b32 m0, s60
	ds_read_b128 v[170:173], v251 offset:49152
	ds_read_b128 v[174:177], v251 offset:50176
	ds_read_b128 v[178:181], v251 offset:51200
	ds_read_b128 v[182:185], v251 offset:52224
	ds_read_b128 v[186:189], v251 offset:53248
	ds_read_b128 v[190:193], v251 offset:54272
	ds_read_b128 v[194:197], v251 offset:55296
	ds_read_b128 v[198:201], v251 offset:56320
	global_load_lds_dwordx4 v[202:203], off
	s_add_i32 m0, s60, 0x2000
	s_add_u32 s58, s58, 0x40080
	v_lshl_add_u64 v[202:203], v[204:205], 0, s[20:21]
	s_addc_u32 s59, s59, 0
	s_add_i32 s60, s78, s27
	global_load_lds_dwordx4 v[202:203], off
	v_lshl_add_u64 v[202:203], s[58:59], 0, v[144:145]
	s_mov_b32 m0, s60
	s_nop 0
	global_load_lds_dwordx4 v[202:203], off
	v_lshl_add_u64 v[202:203], s[58:59], 0, v[160:161]
	s_add_i32 m0, s60, 0x2000
	s_nop 0
	global_load_lds_dwordx4 v[202:203], off
	v_lshl_add_u64 v[202:203], v[206:207], 0, s[20:21]
	s_mov_b32 m0, s69
	s_nop 0
	global_load_lds_dwordx4 v[202:203], off
	v_lshl_add_u64 v[202:203], v[208:209], 0, s[20:21]
	s_mov_b32 m0, s70
	s_nop 0
	global_load_lds_dwordx4 v[202:203], off
	s_waitcnt vmcnt(8)
	s_waitcnt lgkmcnt(0)
	s_barrier
	s_setprio 1
	s_waitcnt lgkmcnt(0)
	v_mfma_f32_16x16x32_bf16 v[76:79], v[56:59], v[170:173], v[76:79]
	v_mfma_f32_16x16x32_bf16 v[72:75], v[64:67], v[170:173], v[72:75]
	v_mfma_f32_16x16x32_bf16 v[52:55], v[56:59], v[178:181], v[52:55]
	v_mfma_f32_16x16x32_bf16 v[44:47], v[64:67], v[178:181], v[44:47]
	v_mfma_f32_16x16x32_bf16 v[28:31], v[56:59], v[186:189], v[28:31]
	v_mfma_f32_16x16x32_bf16 v[24:27], v[64:67], v[186:189], v[24:27]
	v_mfma_f32_16x16x32_bf16 v[12:15], v[56:59], v[194:197], v[12:15]
	v_mfma_f32_16x16x32_bf16 v[8:11], v[64:67], v[194:197], v[8:11]
	v_mfma_f32_16x16x32_bf16 v[76:79], v[60:63], v[174:177], v[76:79]
	v_mfma_f32_16x16x32_bf16 v[72:75], v[68:71], v[174:177], v[72:75]
	v_mfma_f32_16x16x32_bf16 v[52:55], v[60:63], v[182:185], v[52:55]
	v_mfma_f32_16x16x32_bf16 v[44:47], v[68:71], v[182:185], v[44:47]
	v_mfma_f32_16x16x32_bf16 v[28:31], v[60:63], v[190:193], v[28:31]
	v_mfma_f32_16x16x32_bf16 v[24:27], v[68:71], v[190:193], v[24:27]
	v_mfma_f32_16x16x32_bf16 v[12:15], v[60:63], v[198:201], v[12:15]
	v_mfma_f32_16x16x32_bf16 v[8:11], v[68:71], v[198:201], v[8:11]
	v_mfma_f32_16x16x32_bf16 v[40:43], v[146:149], v[170:173], v[40:43]
	v_mfma_f32_16x16x32_bf16 v[64:67], v[150:153], v[174:177], v[40:43]
	v_mfma_f32_16x16x32_bf16 v[40:43], v[154:157], v[170:173], v[48:51]
	v_mfma_f32_16x16x32_bf16 v[36:39], v[146:149], v[178:181], v[36:39]
	v_mfma_f32_16x16x32_bf16 v[32:35], v[154:157], v[178:181], v[32:35]
	v_mfma_f32_16x16x32_bf16 v[20:23], v[146:149], v[186:189], v[20:23]
	v_mfma_f32_16x16x32_bf16 v[16:19], v[154:157], v[186:189], v[16:19]
	v_mfma_f32_16x16x32_bf16 v[4:7], v[146:149], v[194:197], v[4:7]
	v_mfma_f32_16x16x32_bf16 v[0:3], v[154:157], v[194:197], v[0:3]
	v_mfma_f32_16x16x32_bf16 v[56:59], v[166:169], v[174:177], v[40:43]
	v_mfma_f32_16x16x32_bf16 v[36:39], v[150:153], v[182:185], v[36:39]
	v_mfma_f32_16x16x32_bf16 v[32:35], v[166:169], v[182:185], v[32:35]
	v_mfma_f32_16x16x32_bf16 v[20:23], v[150:153], v[190:193], v[20:23]
	v_mfma_f32_16x16x32_bf16 v[16:19], v[166:169], v[190:193], v[16:19]
	v_mfma_f32_16x16x32_bf16 v[4:7], v[150:153], v[198:201], v[4:7]
	v_mfma_f32_16x16x32_bf16 v[0:3], v[166:169], v[198:201], v[0:3]
	s_setprio 0
	s_barrier
	s_add_i32 s76, s76, 2
	s_add_u32 s56, s56, 0x100
	s_addc_u32 s57, s57, 0
	s_add_u32 s51, s51, 0x100
	s_addc_u32 s75, s75, 0
	s_cmp_gt_u32 s76, 13
	s_cbranch_scc0 .LBB0_39
	s_and_b64 vcc, exec, s[44:45]
	s_cbranch_vccz .LBB0_42
	s_barrier

.LBB0_346:
	s_add_u32 s46, s44, 0xfffc0080
	s_addc_u32 s47, s45, -1
	s_add_i32 s63, 0, 0x10000
	s_cmp_eq_u32 s62, 12
	s_cselect_b32 s49, s4, s47
	s_cselect_b32 s48, s5, s46
	v_add_u32_e32 v142, s63, v136
	s_cselect_b32 s47, s25, s61
	s_cselect_b32 s46, s39, s60
	s_add_i32 s68, 0, 0x14000
	ds_read_b128 v[138:141], v142
	ds_read_b128 v[146:149], v142 offset:1024
	ds_read_b128 v[150:153], v142 offset:2048
	ds_read_b128 v[154:157], v142 offset:3072
	v_add_u32_e32 v142, s68, v136
	ds_read_b128 v[160:163], v142
	ds_read_b128 v[164:167], v142 offset:1024
	ds_read_b128 v[168:171], v142 offset:2048
	ds_read_b128 v[172:175], v142 offset:3072
	v_lshl_add_u64 v[142:143], s[44:45], 0, v[130:131]
	s_add_i32 m0, s17, 0xc000
	ds_read_b128 v[176:179], v137
	ds_read_b128 v[180:183], v137 offset:1024
	ds_read_b128 v[184:187], v137 offset:2048
	ds_read_b128 v[188:191], v137 offset:3072
	ds_read_b128 v[192:195], v137 offset:4096
	ds_read_b128 v[196:199], v137 offset:5120
	ds_read_b128 v[200:203], v137 offset:6144
	ds_read_b128 v[204:207], v137 offset:7168
	global_load_lds_dwordx4 v[142:143], off
	v_lshl_add_u64 v[142:143], s[44:45], 0, v[132:133]
	s_add_i32 m0, s17, 0xe000
	s_nop 0
	global_load_lds_dwordx4 v[142:143], off
	s_waitcnt vmcnt(8)
	s_waitcnt lgkmcnt(0)
	s_barrier
	s_setprio 1
	s_waitcnt lgkmcnt(0)
	v_mfma_f32_16x16x32_bf16 v[124:127], v[138:141], v[176:179], v[124:127]
	v_mfma_f32_16x16x32_bf16 v[120:123], v[150:153], v[176:179], v[120:123]
	v_mfma_f32_16x16x32_bf16 v[116:119], v[138:141], v[184:187], v[116:119]
	v_mfma_f32_16x16x32_bf16 v[108:111], v[150:153], v[184:187], v[108:111]
	v_mfma_f32_16x16x32_bf16 v[92:95], v[138:141], v[192:195], v[92:95]
	v_mfma_f32_16x16x32_bf16 v[84:87], v[150:153], v[192:195], v[84:87]
	v_mfma_f32_16x16x32_bf16 v[60:63], v[138:141], v[200:203], v[60:63]
	v_mfma_f32_16x16x32_bf16 v[52:55], v[150:153], v[200:203], v[52:55]
	v_mfma_f32_16x16x32_bf16 v[124:127], v[146:149], v[180:183], v[124:127]
	v_mfma_f32_16x16x32_bf16 v[120:123], v[154:157], v[180:183], v[120:123]
	v_mfma_f32_16x16x32_bf16 v[116:119], v[146:149], v[188:191], v[116:119]
	v_mfma_f32_16x16x32_bf16 v[108:111], v[154:157], v[188:191], v[108:111]
	v_mfma_f32_16x16x32_bf16 v[92:95], v[146:149], v[196:199], v[92:95]
	v_mfma_f32_16x16x32_bf16 v[84:87], v[154:157], v[196:199], v[84:87]
	v_mfma_f32_16x16x32_bf16 v[60:63], v[146:149], v[204:207], v[60:63]
	v_mfma_f32_16x16x32_bf16 v[52:55], v[154:157], v[204:207], v[52:55]
	v_mfma_f32_16x16x32_bf16 v[112:115], v[160:163], v[176:179], v[112:115]
	v_mfma_f32_16x16x32_bf16 v[104:107], v[168:171], v[176:179], v[104:107]
	v_mfma_f32_16x16x32_bf16 v[88:91], v[160:163], v[184:187], v[88:91]
	v_mfma_f32_16x16x32_bf16 v[80:83], v[168:171], v[184:187], v[80:83]
	v_mfma_f32_16x16x32_bf16 v[56:59], v[160:163], v[192:195], v[56:59]
	v_mfma_f32_16x16x32_bf16 v[48:51], v[168:171], v[192:195], v[48:51]
	v_mfma_f32_16x16x32_bf16 v[28:31], v[160:163], v[200:203], v[28:31]
	v_mfma_f32_16x16x32_bf16 v[24:27], v[168:171], v[200:203], v[24:27]
	v_mfma_f32_16x16x32_bf16 v[112:115], v[164:167], v[180:183], v[112:115]
	v_mfma_f32_16x16x32_bf16 v[104:107], v[172:175], v[180:183], v[104:107]
	v_mfma_f32_16x16x32_bf16 v[88:91], v[164:167], v[188:191], v[88:91]
	v_mfma_f32_16x16x32_bf16 v[80:83], v[172:175], v[188:191], v[80:83]
	v_mfma_f32_16x16x32_bf16 v[56:59], v[164:167], v[196:199], v[56:59]
	v_mfma_f32_16x16x32_bf16 v[48:51], v[172:175], v[196:199], v[48:51]
	v_mfma_f32_16x16x32_bf16 v[28:31], v[164:167], v[204:207], v[28:31]
	v_mfma_f32_16x16x32_bf16 v[24:27], v[172:175], v[204:207], v[24:27]
	s_setprio 0
	s_barrier
	s_add_i32 s63, s63, s27
	v_lshl_add_u64 v[142:143], s[46:47], 0, v[144:145]
	s_mov_b32 m0, s63
	ds_read_b128 v[176:179], v137 offset:16384
	ds_read_b128 v[180:183], v137 offset:17408
	ds_read_b128 v[184:187], v137 offset:18432
	ds_read_b128 v[188:191], v137 offset:19456
	ds_read_b128 v[192:195], v137 offset:20480
	ds_read_b128 v[196:199], v137 offset:21504
	ds_read_b128 v[200:203], v137 offset:22528
	ds_read_b128 v[204:207], v137 offset:23552
	global_load_lds_dwordx4 v[142:143], off
	s_add_i32 m0, s63, 0x2000
	s_add_u32 s64, s46, 0x40000
	v_lshl_add_u64 v[208:209], s[46:47], 0, v[128:129]
	s_addc_u32 s65, s47, 0
	s_add_i32 s63, s68, s27
	global_load_lds_dwordx4 v[208:209], off
	v_lshl_add_u64 v[210:211], s[64:65], 0, v[144:145]
	s_mov_b32 m0, s63
	v_lshl_add_u64 v[212:213], s[48:49], 0, v[128:129]
	global_load_lds_dwordx4 v[210:211], off
	v_lshl_add_u64 v[210:211], s[64:65], 0, v[128:129]
	s_add_i32 m0, s63, 0x2000
	s_nop 0
	global_load_lds_dwordx4 v[210:211], off
	v_lshl_add_u64 v[210:211], s[48:49], 0, v[144:145]
	s_mov_b32 m0, s17
	s_nop 0
	global_load_lds_dwordx4 v[210:211], off
	s_mov_b32 m0, s50
	s_nop 0
	global_load_lds_dwordx4 v[212:213], off
	s_waitcnt vmcnt(8)
	s_waitcnt lgkmcnt(0)
	s_barrier
	s_setprio 1
	s_waitcnt lgkmcnt(0)
	v_mfma_f32_16x16x32_bf16 v[100:103], v[138:141], v[176:179], v[100:103]
	v_mfma_f32_16x16x32_bf16 v[96:99], v[150:153], v[176:179], v[96:99]
	v_mfma_f32_16x16x32_bf16 v[76:79], v[138:141], v[184:187], v[76:79]
	v_mfma_f32_16x16x32_bf16 v[68:71], v[150:153], v[184:187], v[68:71]
	v_mfma_f32_16x16x32_bf16 v[44:47], v[138:141], v[192:195], v[44:47]
	v_mfma_f32_16x16x32_bf16 v[36:39], v[150:153], v[192:195], v[36:39]
	v_mfma_f32_16x16x32_bf16 v[20:23], v[138:141], v[200:203], v[20:23]
	v_mfma_f32_16x16x32_bf16 v[12:15], v[150:153], v[200:203], v[12:15]
	v_mfma_f32_16x16x32_bf16 v[100:103], v[146:149], v[180:183], v[100:103]
	v_mfma_f32_16x16x32_bf16 v[96:99], v[154:157], v[180:183], v[96:99]
	v_mfma_f32_16x16x32_bf16 v[76:79], v[146:149], v[188:191], v[76:79]
	v_mfma_f32_16x16x32_bf16 v[68:71], v[154:157], v[188:191], v[68:71]
	v_mfma_f32_16x16x32_bf16 v[44:47], v[146:149], v[196:199], v[44:47]
	v_mfma_f32_16x16x32_bf16 v[36:39], v[154:157], v[196:199], v[36:39]
	v_mfma_f32_16x16x32_bf16 v[20:23], v[146:149], v[204:207], v[20:23]
	v_mfma_f32_16x16x32_bf16 v[12:15], v[154:157], v[204:207], v[12:15]
	v_mfma_f32_16x16x32_bf16 v[72:75], v[160:163], v[176:179], v[72:75]
	v_mfma_f32_16x16x32_bf16 v[64:67], v[168:171], v[176:179], v[64:67]
	v_mfma_f32_16x16x32_bf16 v[40:43], v[160:163], v[184:187], v[40:43]
	v_mfma_f32_16x16x32_bf16 v[32:35], v[168:171], v[184:187], v[32:35]
	v_mfma_f32_16x16x32_bf16 v[16:19], v[160:163], v[192:195], v[16:19]
	v_mfma_f32_16x16x32_bf16 v[8:11], v[168:171], v[192:195], v[8:11]
	v_mfma_f32_16x16x32_bf16 v[4:7], v[160:163], v[200:203], v[4:7]
	v_mfma_f32_16x16x32_bf16 v[0:3], v[168:171], v[200:203], v[0:3]
	v_mfma_f32_16x16x32_bf16 v[72:75], v[164:167], v[180:183], v[72:75]
	v_mfma_f32_16x16x32_bf16 v[64:67], v[172:175], v[180:183], v[64:67]
	v_mfma_f32_16x16x32_bf16 v[40:43], v[164:167], v[188:191], v[40:43]
	v_mfma_f32_16x16x32_bf16 v[32:35], v[172:175], v[188:191], v[32:35]
	v_mfma_f32_16x16x32_bf16 v[16:19], v[164:167], v[196:199], v[16:19]
	v_mfma_f32_16x16x32_bf16 v[8:11], v[172:175], v[196:199], v[8:11]
	v_mfma_f32_16x16x32_bf16 v[4:7], v[164:167], v[204:207], v[4:7]
	v_mfma_f32_16x16x32_bf16 v[0:3], v[172:175], v[204:207], v[0:3]
	s_setprio 0
	s_barrier
	s_add_i32 s63, 0, 0x18000
	s_add_i32 s64, 0, 0x1c000
	v_add_u32_e32 v154, s63, v136
	v_add_u32_e32 v159, s64, v136
	ds_read_b128 v[138:141], v154
	ds_read_b128 v[146:149], v154 offset:1024
	ds_read_b128 v[150:153], v154 offset:2048
	ds_read_b128 v[154:157], v154 offset:3072
	ds_read_b128 v[160:163], v159
	ds_read_b128 v[164:167], v159 offset:1024
	ds_read_b128 v[168:171], v159 offset:2048
	ds_read_b128 v[172:175], v159 offset:3072
	s_add_u32 s48, s48, 0x40000
	s_addc_u32 s49, s49, 0
	s_mov_b32 m0, s51
	v_lshl_add_u64 v[214:215], s[48:49], 0, v[144:145]
	ds_read_b128 v[176:179], v137 offset:32768
	ds_read_b128 v[180:183], v137 offset:33792
	ds_read_b128 v[184:187], v137 offset:34816
	ds_read_b128 v[188:191], v137 offset:35840
	ds_read_b128 v[192:195], v137 offset:36864
	ds_read_b128 v[196:199], v137 offset:37888
	ds_read_b128 v[200:203], v137 offset:38912
	ds_read_b128 v[204:207], v137 offset:39936
	global_load_lds_dwordx4 v[214:215], off
	v_lshl_add_u64 v[214:215], s[48:49], 0, v[128:129]
	s_mov_b32 m0, s52
	s_nop 0
	global_load_lds_dwordx4 v[214:215], off
	s_waitcnt vmcnt(8)
	s_waitcnt lgkmcnt(0)
	s_barrier
	s_setprio 1
	s_waitcnt lgkmcnt(0)
	v_mfma_f32_16x16x32_bf16 v[124:127], v[138:141], v[176:179], v[124:127]
	v_mfma_f32_16x16x32_bf16 v[120:123], v[150:153], v[176:179], v[120:123]
	v_mfma_f32_16x16x32_bf16 v[116:119], v[138:141], v[184:187], v[116:119]
	v_mfma_f32_16x16x32_bf16 v[108:111], v[150:153], v[184:187], v[108:111]
	v_mfma_f32_16x16x32_bf16 v[92:95], v[138:141], v[192:195], v[92:95]
	v_mfma_f32_16x16x32_bf16 v[84:87], v[150:153], v[192:195], v[84:87]
	v_mfma_f32_16x16x32_bf16 v[60:63], v[138:141], v[200:203], v[60:63]
	v_mfma_f32_16x16x32_bf16 v[52:55], v[150:153], v[200:203], v[52:55]
	v_mfma_f32_16x16x32_bf16 v[124:127], v[146:149], v[180:183], v[124:127]
	v_mfma_f32_16x16x32_bf16 v[120:123], v[154:157], v[180:183], v[120:123]
	v_mfma_f32_16x16x32_bf16 v[116:119], v[146:149], v[188:191], v[116:119]
	v_mfma_f32_16x16x32_bf16 v[108:111], v[154:157], v[188:191], v[108:111]
	v_mfma_f32_16x16x32_bf16 v[92:95], v[146:149], v[196:199], v[92:95]
	v_mfma_f32_16x16x32_bf16 v[84:87], v[154:157], v[196:199], v[84:87]
	v_mfma_f32_16x16x32_bf16 v[60:63], v[146:149], v[204:207], v[60:63]
	v_mfma_f32_16x16x32_bf16 v[52:55], v[154:157], v[204:207], v[52:55]
	v_mfma_f32_16x16x32_bf16 v[112:115], v[160:163], v[176:179], v[112:115]
	v_mfma_f32_16x16x32_bf16 v[104:107], v[168:171], v[176:179], v[104:107]
	v_mfma_f32_16x16x32_bf16 v[88:91], v[160:163], v[184:187], v[88:91]
	v_mfma_f32_16x16x32_bf16 v[80:83], v[168:171], v[184:187], v[80:83]
	v_mfma_f32_16x16x32_bf16 v[56:59], v[160:163], v[192:195], v[56:59]
	v_mfma_f32_16x16x32_bf16 v[48:51], v[168:171], v[192:195], v[48:51]
	v_mfma_f32_16x16x32_bf16 v[28:31], v[160:163], v[200:203], v[28:31]
	v_mfma_f32_16x16x32_bf16 v[24:27], v[168:171], v[200:203], v[24:27]
	v_mfma_f32_16x16x32_bf16 v[112:115], v[164:167], v[180:183], v[112:115]
	v_mfma_f32_16x16x32_bf16 v[104:107], v[172:175], v[180:183], v[104:107]
	v_mfma_f32_16x16x32_bf16 v[88:91], v[164:167], v[188:191], v[88:91]
	v_mfma_f32_16x16x32_bf16 v[80:83], v[172:175], v[188:191], v[80:83]
	v_mfma_f32_16x16x32_bf16 v[56:59], v[164:167], v[196:199], v[56:59]
	v_mfma_f32_16x16x32_bf16 v[48:51], v[172:175], v[196:199], v[48:51]
	v_mfma_f32_16x16x32_bf16 v[28:31], v[164:167], v[204:207], v[28:31]
	v_mfma_f32_16x16x32_bf16 v[24:27], v[172:175], v[204:207], v[24:27]
	s_setprio 0
	s_barrier
	s_add_i32 s48, s63, s27
	v_lshl_add_u64 v[142:143], v[142:143], 0, s[20:21]
	s_mov_b32 m0, s48
	ds_read_b128 v[176:179], v137 offset:49152
	ds_read_b128 v[180:183], v137 offset:50176
	ds_read_b128 v[184:187], v137 offset:51200
	ds_read_b128 v[188:191], v137 offset:52224
	ds_read_b128 v[192:195], v137 offset:53248
	ds_read_b128 v[196:199], v137 offset:54272
	ds_read_b128 v[200:203], v137 offset:55296
	ds_read_b128 v[204:207], v137 offset:56320
	global_load_lds_dwordx4 v[142:143], off
	s_add_i32 m0, s48, 0x2000
	s_add_u32 s46, s46, 0x40080
	v_lshl_add_u64 v[142:143], v[208:209], 0, s[20:21]
	s_addc_u32 s47, s47, 0
	s_add_i32 s48, s64, s27
	global_load_lds_dwordx4 v[142:143], off
	v_lshl_add_u64 v[142:143], s[46:47], 0, v[144:145]
	s_mov_b32 m0, s48
	s_nop 0
	global_load_lds_dwordx4 v[142:143], off
	v_lshl_add_u64 v[142:143], s[46:47], 0, v[128:129]
	s_add_i32 m0, s48, 0x2000
	s_nop 0
	global_load_lds_dwordx4 v[142:143], off
	v_lshl_add_u64 v[142:143], v[210:211], 0, s[20:21]
	s_mov_b32 m0, s55
	s_nop 0
	global_load_lds_dwordx4 v[142:143], off
	v_lshl_add_u64 v[142:143], v[212:213], 0, s[20:21]
	s_mov_b32 m0, s56
	s_nop 0
	global_load_lds_dwordx4 v[142:143], off
	s_waitcnt vmcnt(8)
	s_waitcnt lgkmcnt(0)
	s_barrier
	s_setprio 1
	s_waitcnt lgkmcnt(0)
	v_mfma_f32_16x16x32_bf16 v[100:103], v[138:141], v[176:179], v[100:103]
	v_mfma_f32_16x16x32_bf16 v[96:99], v[150:153], v[176:179], v[96:99]
	v_mfma_f32_16x16x32_bf16 v[76:79], v[138:141], v[184:187], v[76:79]
	v_mfma_f32_16x16x32_bf16 v[68:71], v[150:153], v[184:187], v[68:71]
	v_mfma_f32_16x16x32_bf16 v[44:47], v[138:141], v[192:195], v[44:47]
	v_mfma_f32_16x16x32_bf16 v[36:39], v[150:153], v[192:195], v[36:39]
	v_mfma_f32_16x16x32_bf16 v[20:23], v[138:141], v[200:203], v[20:23]
	v_mfma_f32_16x16x32_bf16 v[12:15], v[150:153], v[200:203], v[12:15]
	v_mfma_f32_16x16x32_bf16 v[100:103], v[146:149], v[180:183], v[100:103]
	v_mfma_f32_16x16x32_bf16 v[96:99], v[154:157], v[180:183], v[96:99]
	v_mfma_f32_16x16x32_bf16 v[76:79], v[146:149], v[188:191], v[76:79]
	v_mfma_f32_16x16x32_bf16 v[68:71], v[154:157], v[188:191], v[68:71]
	v_mfma_f32_16x16x32_bf16 v[44:47], v[146:149], v[196:199], v[44:47]
	v_mfma_f32_16x16x32_bf16 v[36:39], v[154:157], v[196:199], v[36:39]
	v_mfma_f32_16x16x32_bf16 v[20:23], v[146:149], v[204:207], v[20:23]
	v_mfma_f32_16x16x32_bf16 v[12:15], v[154:157], v[204:207], v[12:15]
	v_mfma_f32_16x16x32_bf16 v[72:75], v[160:163], v[176:179], v[72:75]
	v_mfma_f32_16x16x32_bf16 v[64:67], v[168:171], v[176:179], v[64:67]
	v_mfma_f32_16x16x32_bf16 v[40:43], v[160:163], v[184:187], v[40:43]
	v_mfma_f32_16x16x32_bf16 v[32:35], v[168:171], v[184:187], v[32:35]
	v_mfma_f32_16x16x32_bf16 v[16:19], v[160:163], v[192:195], v[16:19]
	v_mfma_f32_16x16x32_bf16 v[8:11], v[168:171], v[192:195], v[8:11]
	v_mfma_f32_16x16x32_bf16 v[4:7], v[160:163], v[200:203], v[4:7]
	v_mfma_f32_16x16x32_bf16 v[0:3], v[168:171], v[200:203], v[0:3]
	v_mfma_f32_16x16x32_bf16 v[72:75], v[164:167], v[180:183], v[72:75]
	v_mfma_f32_16x16x32_bf16 v[64:67], v[172:175], v[180:183], v[64:67]
	v_mfma_f32_16x16x32_bf16 v[40:43], v[164:167], v[188:191], v[40:43]
	v_mfma_f32_16x16x32_bf16 v[32:35], v[172:175], v[188:191], v[32:35]
	v_mfma_f32_16x16x32_bf16 v[16:19], v[164:167], v[196:199], v[16:19]
	v_mfma_f32_16x16x32_bf16 v[8:11], v[172:175], v[196:199], v[8:11]
	v_mfma_f32_16x16x32_bf16 v[4:7], v[164:167], v[204:207], v[4:7]
	v_mfma_f32_16x16x32_bf16 v[0:3], v[172:175], v[204:207], v[0:3]
	s_setprio 0
	s_barrier
	s_add_i32 s62, s62, 2
	s_add_u32 s44, s44, 0x100
	s_addc_u32 s45, s45, 0
	s_add_u32 s60, s60, 0x100
	s_addc_u32 s61, s61, 0
	s_cmp_gt_u32 s62, 13
	s_cbranch_scc0 .LBB0_346
	s_and_b64 vcc, exec, s[12:13]
	s_cbranch_vccz .LBB0_349
	s_barrier

.LBB0_437:
	s_add_i32 s50, s48, 2
	s_add_u32 s51, s40, 0x80
	s_addc_u32 s49, s41, 0
	s_add_i32 s76, 0, 0x10000
	s_cmp_eq_u32 s64, s48
	s_cselect_b32 s49, s45, s49
	s_cselect_b32 s48, s44, s51
	s_cselect_b32 s75, s47, s5
	s_cselect_b32 s74, s46, s4
	s_add_i32 s51, 0, 0x14000
	v_add_u32_e32 v120, s76, v201
	v_add_u32_e32 v166, s51, v201
	ds_read_b128 v[108:111], v120
	ds_read_b128 v[112:115], v120 offset:1024
	ds_read_b128 v[116:119], v120 offset:2048
	ds_read_b128 v[120:123], v120 offset:3072
	ds_read_b128 v[146:149], v166
	ds_read_b128 v[150:153], v166 offset:1024
	ds_read_b128 v[154:157], v166 offset:2048
	ds_read_b128 v[166:169], v166 offset:3072
	v_lshl_add_u64 v[198:199], s[40:41], 0, v[162:163]
	s_add_i32 m0, s55, 0xc000
	ds_read_b128 v[170:173], v202
	ds_read_b128 v[174:177], v202 offset:1024
	ds_read_b128 v[178:181], v202 offset:2048
	ds_read_b128 v[182:185], v202 offset:3072
	ds_read_b128 v[186:189], v202 offset:4096
	ds_read_b128 v[190:193], v202 offset:5120
	ds_read_b128 v[194:197], v202 offset:6144
	ds_read_b128 v[204:207], v202 offset:7168
	global_load_lds_dwordx4 v[198:199], off
	v_lshl_add_u64 v[198:199], s[40:41], 0, v[164:165]
	s_add_i32 m0, s55, 0xe000
	s_nop 0
	global_load_lds_dwordx4 v[198:199], off
	s_waitcnt vmcnt(8)
	s_waitcnt lgkmcnt(0)
	s_barrier
	s_setprio 1
	s_waitcnt lgkmcnt(0)
	v_mfma_f32_16x16x32_bf16 v[140:143], v[108:111], v[170:173], v[140:143]
	v_mfma_f32_16x16x32_bf16 v[136:139], v[116:119], v[170:173], v[136:139]
	v_mfma_f32_16x16x32_bf16 v[132:135], v[108:111], v[178:181], v[132:135]
	v_mfma_f32_16x16x32_bf16 v[104:107], v[116:119], v[178:181], v[104:107]
	v_mfma_f32_16x16x32_bf16 v[96:99], v[108:111], v[186:189], v[96:99]
	v_mfma_f32_16x16x32_bf16 v[88:91], v[116:119], v[186:189], v[88:91]
	v_mfma_f32_16x16x32_bf16 v[80:83], v[108:111], v[194:197], v[80:83]
	v_mfma_f32_16x16x32_bf16 v[72:75], v[116:119], v[194:197], v[72:75]
	v_mfma_f32_16x16x32_bf16 v[140:143], v[112:115], v[174:177], v[140:143]
	v_mfma_f32_16x16x32_bf16 v[136:139], v[120:123], v[174:177], v[136:139]
	v_mfma_f32_16x16x32_bf16 v[132:135], v[112:115], v[182:185], v[132:135]
	v_mfma_f32_16x16x32_bf16 v[104:107], v[120:123], v[182:185], v[104:107]
	v_mfma_f32_16x16x32_bf16 v[96:99], v[112:115], v[190:193], v[96:99]
	v_mfma_f32_16x16x32_bf16 v[88:91], v[120:123], v[190:193], v[88:91]
	v_mfma_f32_16x16x32_bf16 v[80:83], v[112:115], v[204:207], v[80:83]
	v_mfma_f32_16x16x32_bf16 v[72:75], v[120:123], v[204:207], v[72:75]
	v_mfma_f32_16x16x32_bf16 v[128:131], v[146:149], v[170:173], v[128:131]
	v_mfma_f32_16x16x32_bf16 v[124:127], v[154:157], v[170:173], v[124:127]
	v_mfma_f32_16x16x32_bf16 v[100:103], v[146:149], v[178:181], v[100:103]
	v_mfma_f32_16x16x32_bf16 v[92:95], v[154:157], v[178:181], v[92:95]
	v_mfma_f32_16x16x32_bf16 v[84:87], v[146:149], v[186:189], v[84:87]
	v_mfma_f32_16x16x32_bf16 v[76:79], v[154:157], v[186:189], v[76:79]
	v_mfma_f32_16x16x32_bf16 v[68:71], v[146:149], v[194:197], v[68:71]
	v_mfma_f32_16x16x32_bf16 v[64:67], v[154:157], v[194:197], v[64:67]
	v_mfma_f32_16x16x32_bf16 v[128:131], v[150:153], v[174:177], v[128:131]
	v_mfma_f32_16x16x32_bf16 v[124:127], v[166:169], v[174:177], v[124:127]
	v_mfma_f32_16x16x32_bf16 v[100:103], v[150:153], v[182:185], v[100:103]
	v_mfma_f32_16x16x32_bf16 v[92:95], v[166:169], v[182:185], v[92:95]
	v_mfma_f32_16x16x32_bf16 v[84:87], v[150:153], v[190:193], v[84:87]
	v_mfma_f32_16x16x32_bf16 v[76:79], v[166:169], v[190:193], v[76:79]
	v_mfma_f32_16x16x32_bf16 v[68:71], v[150:153], v[204:207], v[68:71]
	v_mfma_f32_16x16x32_bf16 v[64:67], v[166:169], v[204:207], v[64:67]
	s_setprio 0
	s_barrier
	s_add_i32 s76, s76, s52
	v_lshl_add_u64 v[198:199], s[74:75], 0, v[144:145]
	s_mov_b32 m0, s76
	ds_read_b128 v[170:173], v202 offset:16384
	ds_read_b128 v[174:177], v202 offset:17408
	ds_read_b128 v[178:181], v202 offset:18432
	ds_read_b128 v[182:185], v202 offset:19456
	ds_read_b128 v[186:189], v202 offset:20480
	ds_read_b128 v[190:193], v202 offset:21504
	ds_read_b128 v[194:197], v202 offset:22528
	ds_read_b128 v[204:207], v202 offset:23552
	global_load_lds_dwordx4 v[198:199], off
	s_add_i32 m0, s76, 0x2000
	v_lshl_add_u64 v[208:209], s[74:75], 0, v[160:161]
	s_add_u32 s74, s74, s30
	s_addc_u32 s75, s75, 0
	s_add_i32 s51, s51, s52
	global_load_lds_dwordx4 v[208:209], off
	v_lshl_add_u64 v[210:211], s[74:75], 0, v[144:145]
	s_mov_b32 m0, s51
	v_lshl_add_u64 v[212:213], s[74:75], 0, v[160:161]
	global_load_lds_dwordx4 v[210:211], off
	s_add_i32 m0, s51, 0x2000
	v_lshl_add_u64 v[214:215], s[48:49], 0, v[144:145]
	global_load_lds_dwordx4 v[212:213], off
	s_mov_b32 m0, s55
	v_lshl_add_u64 v[216:217], s[48:49], 0, v[160:161]
	global_load_lds_dwordx4 v[214:215], off
	s_mov_b32 m0, s56
	s_nop 0
	global_load_lds_dwordx4 v[216:217], off
	s_waitcnt vmcnt(8)
	s_waitcnt lgkmcnt(0)
	s_barrier
	s_setprio 1
	s_waitcnt lgkmcnt(0)
	v_mfma_f32_16x16x32_bf16 v[60:63], v[108:111], v[170:173], v[60:63]
	v_mfma_f32_16x16x32_bf16 v[56:59], v[116:119], v[170:173], v[56:59]
	v_mfma_f32_16x16x32_bf16 v[48:51], v[108:111], v[178:181], v[48:51]
	v_mfma_f32_16x16x32_bf16 v[40:43], v[116:119], v[178:181], v[40:43]
	v_mfma_f32_16x16x32_bf16 v[32:35], v[108:111], v[186:189], v[32:35]
	v_mfma_f32_16x16x32_bf16 v[24:27], v[116:119], v[186:189], v[24:27]
	v_mfma_f32_16x16x32_bf16 v[16:19], v[108:111], v[194:197], v[16:19]
	v_mfma_f32_16x16x32_bf16 v[8:11], v[116:119], v[194:197], v[8:11]
	v_mfma_f32_16x16x32_bf16 v[60:63], v[112:115], v[174:177], v[60:63]
	v_mfma_f32_16x16x32_bf16 v[56:59], v[120:123], v[174:177], v[56:59]
	v_mfma_f32_16x16x32_bf16 v[48:51], v[112:115], v[182:185], v[48:51]
	v_mfma_f32_16x16x32_bf16 v[40:43], v[120:123], v[182:185], v[40:43]
	v_mfma_f32_16x16x32_bf16 v[32:35], v[112:115], v[190:193], v[32:35]
	v_mfma_f32_16x16x32_bf16 v[24:27], v[120:123], v[190:193], v[24:27]
	v_mfma_f32_16x16x32_bf16 v[16:19], v[112:115], v[204:207], v[16:19]
	v_mfma_f32_16x16x32_bf16 v[8:11], v[120:123], v[204:207], v[8:11]
	v_mfma_f32_16x16x32_bf16 v[52:55], v[146:149], v[170:173], v[52:55]
	v_mfma_f32_16x16x32_bf16 v[44:47], v[154:157], v[170:173], v[44:47]
	v_mfma_f32_16x16x32_bf16 v[36:39], v[146:149], v[178:181], v[36:39]
	v_mfma_f32_16x16x32_bf16 v[28:31], v[154:157], v[178:181], v[28:31]
	v_mfma_f32_16x16x32_bf16 v[20:23], v[146:149], v[186:189], v[20:23]
	v_mfma_f32_16x16x32_bf16 v[12:15], v[154:157], v[186:189], v[12:15]
	v_mfma_f32_16x16x32_bf16 v[4:7], v[146:149], v[194:197], v[4:7]
	v_mfma_f32_16x16x32_bf16 v[0:3], v[154:157], v[194:197], v[0:3]
	v_mfma_f32_16x16x32_bf16 v[52:55], v[150:153], v[174:177], v[52:55]
	v_mfma_f32_16x16x32_bf16 v[44:47], v[166:169], v[174:177], v[44:47]
	v_mfma_f32_16x16x32_bf16 v[36:39], v[150:153], v[182:185], v[36:39]
	v_mfma_f32_16x16x32_bf16 v[28:31], v[166:169], v[182:185], v[28:31]
	v_mfma_f32_16x16x32_bf16 v[20:23], v[150:153], v[190:193], v[20:23]
	v_mfma_f32_16x16x32_bf16 v[12:15], v[166:169], v[190:193], v[12:15]
	v_mfma_f32_16x16x32_bf16 v[4:7], v[150:153], v[204:207], v[4:7]
	v_mfma_f32_16x16x32_bf16 v[0:3], v[166:169], v[204:207], v[0:3]
	s_setprio 0
	s_barrier
	s_add_i32 s51, 0, 0x18000
	s_add_i32 s74, 0, 0x1c000
	v_add_u32_e32 v120, s51, v201
	v_add_u32_e32 v166, s74, v201
	ds_read_b128 v[108:111], v120
	ds_read_b128 v[112:115], v120 offset:1024
	ds_read_b128 v[116:119], v120 offset:2048
	ds_read_b128 v[120:123], v120 offset:3072
	ds_read_b128 v[146:149], v166
	ds_read_b128 v[150:153], v166 offset:1024
	ds_read_b128 v[154:157], v166 offset:2048
	ds_read_b128 v[166:169], v166 offset:3072
	s_add_u32 s48, s48, s30
	s_addc_u32 s49, s49, 0
	s_mov_b32 m0, s57
	v_lshl_add_u64 v[218:219], s[48:49], 0, v[144:145]
	ds_read_b128 v[170:173], v202 offset:32768
	ds_read_b128 v[174:177], v202 offset:33792
	ds_read_b128 v[178:181], v202 offset:34816
	ds_read_b128 v[182:185], v202 offset:35840
	ds_read_b128 v[186:189], v202 offset:36864
	ds_read_b128 v[190:193], v202 offset:37888
	ds_read_b128 v[194:197], v202 offset:38912
	ds_read_b128 v[204:207], v202 offset:39936
	global_load_lds_dwordx4 v[218:219], off
	v_lshl_add_u64 v[218:219], s[48:49], 0, v[160:161]
	s_mov_b32 m0, s58
	s_nop 0
	global_load_lds_dwordx4 v[218:219], off
	s_waitcnt vmcnt(8)
	s_waitcnt lgkmcnt(0)
	s_barrier
	s_setprio 1
	s_waitcnt lgkmcnt(0)
	v_mfma_f32_16x16x32_bf16 v[140:143], v[108:111], v[170:173], v[140:143]
	v_mfma_f32_16x16x32_bf16 v[136:139], v[116:119], v[170:173], v[136:139]
	v_mfma_f32_16x16x32_bf16 v[132:135], v[108:111], v[178:181], v[132:135]
	v_mfma_f32_16x16x32_bf16 v[104:107], v[116:119], v[178:181], v[104:107]
	v_mfma_f32_16x16x32_bf16 v[96:99], v[108:111], v[186:189], v[96:99]
	v_mfma_f32_16x16x32_bf16 v[88:91], v[116:119], v[186:189], v[88:91]
	v_mfma_f32_16x16x32_bf16 v[80:83], v[108:111], v[194:197], v[80:83]
	v_mfma_f32_16x16x32_bf16 v[72:75], v[116:119], v[194:197], v[72:75]
	v_mfma_f32_16x16x32_bf16 v[140:143], v[112:115], v[174:177], v[140:143]
	v_mfma_f32_16x16x32_bf16 v[136:139], v[120:123], v[174:177], v[136:139]
	v_mfma_f32_16x16x32_bf16 v[132:135], v[112:115], v[182:185], v[132:135]
	v_mfma_f32_16x16x32_bf16 v[104:107], v[120:123], v[182:185], v[104:107]
	v_mfma_f32_16x16x32_bf16 v[96:99], v[112:115], v[190:193], v[96:99]
	v_mfma_f32_16x16x32_bf16 v[88:91], v[120:123], v[190:193], v[88:91]
	v_mfma_f32_16x16x32_bf16 v[80:83], v[112:115], v[204:207], v[80:83]
	v_mfma_f32_16x16x32_bf16 v[72:75], v[120:123], v[204:207], v[72:75]
	v_mfma_f32_16x16x32_bf16 v[128:131], v[146:149], v[170:173], v[128:131]
	v_mfma_f32_16x16x32_bf16 v[124:127], v[154:157], v[170:173], v[124:127]
	v_mfma_f32_16x16x32_bf16 v[100:103], v[146:149], v[178:181], v[100:103]
	v_mfma_f32_16x16x32_bf16 v[92:95], v[154:157], v[178:181], v[92:95]
	v_mfma_f32_16x16x32_bf16 v[84:87], v[146:149], v[186:189], v[84:87]
	v_mfma_f32_16x16x32_bf16 v[76:79], v[154:157], v[186:189], v[76:79]
	v_mfma_f32_16x16x32_bf16 v[68:71], v[146:149], v[194:197], v[68:71]
	v_mfma_f32_16x16x32_bf16 v[64:67], v[154:157], v[194:197], v[64:67]
	v_mfma_f32_16x16x32_bf16 v[128:131], v[150:153], v[174:177], v[128:131]
	v_mfma_f32_16x16x32_bf16 v[124:127], v[166:169], v[174:177], v[124:127]
	v_mfma_f32_16x16x32_bf16 v[100:103], v[150:153], v[182:185], v[100:103]
	v_mfma_f32_16x16x32_bf16 v[92:95], v[166:169], v[182:185], v[92:95]
	v_mfma_f32_16x16x32_bf16 v[84:87], v[150:153], v[190:193], v[84:87]
	v_mfma_f32_16x16x32_bf16 v[76:79], v[166:169], v[190:193], v[76:79]
	v_mfma_f32_16x16x32_bf16 v[68:71], v[150:153], v[204:207], v[68:71]
	v_mfma_f32_16x16x32_bf16 v[64:67], v[166:169], v[204:207], v[64:67]
	s_setprio 0
	s_barrier
	s_add_i32 s48, s51, s52
	v_lshl_add_u64 v[198:199], v[198:199], 0, s[20:21]
	s_mov_b32 m0, s48
	ds_read_b128 v[170:173], v202 offset:49152
	ds_read_b128 v[174:177], v202 offset:50176
	ds_read_b128 v[178:181], v202 offset:51200
	ds_read_b128 v[182:185], v202 offset:52224
	ds_read_b128 v[186:189], v202 offset:53248
	ds_read_b128 v[190:193], v202 offset:54272
	ds_read_b128 v[194:197], v202 offset:55296
	ds_read_b128 v[204:207], v202 offset:56320
	global_load_lds_dwordx4 v[198:199], off
	v_lshl_add_u64 v[198:199], v[208:209], 0, s[20:21]
	s_add_i32 m0, s48, 0x2000
	s_add_i32 s48, s74, s52
	global_load_lds_dwordx4 v[198:199], off
	v_lshl_add_u64 v[198:199], v[210:211], 0, s[20:21]
	s_mov_b32 m0, s48
	s_nop 0
	global_load_lds_dwordx4 v[198:199], off
	v_lshl_add_u64 v[198:199], v[212:213], 0, s[20:21]
	s_add_i32 m0, s48, 0x2000
	s_nop 0
	global_load_lds_dwordx4 v[198:199], off
	v_lshl_add_u64 v[198:199], v[214:215], 0, s[20:21]
	s_mov_b32 m0, s62
	s_nop 0
	global_load_lds_dwordx4 v[198:199], off
	v_lshl_add_u64 v[198:199], v[216:217], 0, s[20:21]
	s_mov_b32 m0, s63
	s_nop 0
	global_load_lds_dwordx4 v[198:199], off
	s_waitcnt vmcnt(8)
	s_waitcnt lgkmcnt(0)
	s_barrier
	s_setprio 1
	s_waitcnt lgkmcnt(0)
	v_mfma_f32_16x16x32_bf16 v[60:63], v[108:111], v[170:173], v[60:63]
	v_mfma_f32_16x16x32_bf16 v[56:59], v[116:119], v[170:173], v[56:59]
	v_mfma_f32_16x16x32_bf16 v[48:51], v[108:111], v[178:181], v[48:51]
	v_mfma_f32_16x16x32_bf16 v[40:43], v[116:119], v[178:181], v[40:43]
	v_mfma_f32_16x16x32_bf16 v[32:35], v[108:111], v[186:189], v[32:35]
	v_mfma_f32_16x16x32_bf16 v[24:27], v[116:119], v[186:189], v[24:27]
	v_mfma_f32_16x16x32_bf16 v[16:19], v[108:111], v[194:197], v[16:19]
	v_mfma_f32_16x16x32_bf16 v[8:11], v[116:119], v[194:197], v[8:11]
	v_mfma_f32_16x16x32_bf16 v[60:63], v[112:115], v[174:177], v[60:63]
	v_mfma_f32_16x16x32_bf16 v[56:59], v[120:123], v[174:177], v[56:59]
	v_mfma_f32_16x16x32_bf16 v[48:51], v[112:115], v[182:185], v[48:51]
	v_mfma_f32_16x16x32_bf16 v[40:43], v[120:123], v[182:185], v[40:43]
	v_mfma_f32_16x16x32_bf16 v[32:35], v[112:115], v[190:193], v[32:35]
	v_mfma_f32_16x16x32_bf16 v[24:27], v[120:123], v[190:193], v[24:27]
	v_mfma_f32_16x16x32_bf16 v[16:19], v[112:115], v[204:207], v[16:19]
	v_mfma_f32_16x16x32_bf16 v[8:11], v[120:123], v[204:207], v[8:11]
	v_mfma_f32_16x16x32_bf16 v[52:55], v[146:149], v[170:173], v[52:55]
	v_mfma_f32_16x16x32_bf16 v[44:47], v[154:157], v[170:173], v[44:47]
	v_mfma_f32_16x16x32_bf16 v[36:39], v[146:149], v[178:181], v[36:39]
	v_mfma_f32_16x16x32_bf16 v[28:31], v[154:157], v[178:181], v[28:31]
	v_mfma_f32_16x16x32_bf16 v[20:23], v[146:149], v[186:189], v[20:23]
	v_mfma_f32_16x16x32_bf16 v[12:15], v[154:157], v[186:189], v[12:15]
	v_mfma_f32_16x16x32_bf16 v[4:7], v[146:149], v[194:197], v[4:7]
	v_mfma_f32_16x16x32_bf16 v[0:3], v[154:157], v[194:197], v[0:3]
	v_mfma_f32_16x16x32_bf16 v[52:55], v[150:153], v[174:177], v[52:55]
	v_mfma_f32_16x16x32_bf16 v[44:47], v[166:169], v[174:177], v[44:47]
	v_mfma_f32_16x16x32_bf16 v[36:39], v[150:153], v[182:185], v[36:39]
	v_mfma_f32_16x16x32_bf16 v[28:31], v[166:169], v[182:185], v[28:31]
	v_mfma_f32_16x16x32_bf16 v[20:23], v[150:153], v[190:193], v[20:23]
	v_mfma_f32_16x16x32_bf16 v[12:15], v[166:169], v[190:193], v[12:15]
	v_mfma_f32_16x16x32_bf16 v[4:7], v[150:153], v[204:207], v[4:7]
	v_mfma_f32_16x16x32_bf16 v[0:3], v[166:169], v[204:207], v[0:3]
	s_setprio 0
	s_barrier
	s_add_u32 s40, s40, 0x100
	s_addc_u32 s41, s41, 0
	s_add_u32 s4, s4, 0x100
	s_addc_u32 s5, s5, 0
	s_cmp_ge_u32 s50, s59
	s_mov_b32 s48, s50
	s_cbranch_scc0 .LBB0_437
	s_and_b64 vcc, exec, s[24:25]
	s_cbranch_vccz .LBB0_440
	s_barrier

.LBB0_486:
	s_add_u32 s42, s40, 0xfffc0080
	s_addc_u32 s43, s41, -1
	s_add_i32 s79, 0, 0x10000
	s_cmp_eq_u32 s78, 12
	s_cselect_b32 s53, s4, s43
	s_cselect_b32 s52, s5, s42
	v_add_u32_e32 v144, s79, v172
	s_cselect_b32 s43, s27, s47
	s_cselect_b32 s42, s39, s45
	s_add_i32 s82, 0, 0x14000
	ds_read_b128 v[128:131], v144
	ds_read_b128 v[146:149], v144 offset:1024
	ds_read_b128 v[150:153], v144 offset:2048
	ds_read_b128 v[154:157], v144 offset:3072
	v_add_u32_e32 v144, s82, v172
	ds_read_b128 v[160:163], v144
	ds_read_b128 v[164:167], v144 offset:1024
	ds_read_b128 v[174:177], v144 offset:2048
	ds_read_b128 v[178:181], v144 offset:3072
	v_lshl_add_u64 v[168:169], s[40:41], 0, v[140:141]
	s_add_i32 m0, s58, 0xc000
	ds_read_b128 v[182:185], v173
	ds_read_b128 v[186:189], v173 offset:1024
	ds_read_b128 v[190:193], v173 offset:2048
	ds_read_b128 v[194:197], v173 offset:3072
	ds_read_b128 v[198:201], v173 offset:4096
	ds_read_b128 v[202:205], v173 offset:5120
	ds_read_b128 v[206:209], v173 offset:6144
	ds_read_b128 v[210:213], v173 offset:7168
	global_load_lds_dwordx4 v[168:169], off
	v_lshl_add_u64 v[168:169], s[40:41], 0, v[142:143]
	s_add_i32 m0, s58, 0xe000
	s_nop 0
	global_load_lds_dwordx4 v[168:169], off
	s_waitcnt vmcnt(8)
	s_waitcnt lgkmcnt(0)
	s_barrier
	s_setprio 1
	s_waitcnt lgkmcnt(0)
	v_mfma_f32_16x16x32_bf16 v[124:127], v[128:131], v[182:185], v[124:127]
	v_mfma_f32_16x16x32_bf16 v[120:123], v[150:153], v[182:185], v[120:123]
	v_mfma_f32_16x16x32_bf16 v[108:111], v[128:131], v[190:193], v[108:111]
	v_mfma_f32_16x16x32_bf16 v[104:107], v[150:153], v[190:193], v[104:107]
	v_mfma_f32_16x16x32_bf16 v[92:95], v[128:131], v[198:201], v[92:95]
	v_mfma_f32_16x16x32_bf16 v[88:91], v[150:153], v[198:201], v[88:91]
	v_mfma_f32_16x16x32_bf16 v[76:79], v[128:131], v[206:209], v[76:79]
	v_mfma_f32_16x16x32_bf16 v[72:75], v[150:153], v[206:209], v[72:75]
	v_mfma_f32_16x16x32_bf16 v[124:127], v[146:149], v[186:189], v[124:127]
	v_mfma_f32_16x16x32_bf16 v[120:123], v[154:157], v[186:189], v[120:123]
	v_mfma_f32_16x16x32_bf16 v[108:111], v[146:149], v[194:197], v[108:111]
	v_mfma_f32_16x16x32_bf16 v[104:107], v[154:157], v[194:197], v[104:107]
	v_mfma_f32_16x16x32_bf16 v[92:95], v[146:149], v[202:205], v[92:95]
	v_mfma_f32_16x16x32_bf16 v[88:91], v[154:157], v[202:205], v[88:91]
	v_mfma_f32_16x16x32_bf16 v[76:79], v[146:149], v[210:213], v[76:79]
	v_mfma_f32_16x16x32_bf16 v[72:75], v[154:157], v[210:213], v[72:75]
	v_mfma_f32_16x16x32_bf16 v[116:119], v[160:163], v[182:185], v[116:119]
	v_mfma_f32_16x16x32_bf16 v[112:115], v[174:177], v[182:185], v[112:115]
	v_mfma_f32_16x16x32_bf16 v[100:103], v[160:163], v[190:193], v[100:103]
	v_mfma_f32_16x16x32_bf16 v[96:99], v[174:177], v[190:193], v[96:99]
	v_mfma_f32_16x16x32_bf16 v[84:87], v[160:163], v[198:201], v[84:87]
	v_mfma_f32_16x16x32_bf16 v[80:83], v[174:177], v[198:201], v[80:83]
	v_mfma_f32_16x16x32_bf16 v[68:71], v[160:163], v[206:209], v[68:71]
	v_mfma_f32_16x16x32_bf16 v[64:67], v[174:177], v[206:209], v[64:67]
	v_mfma_f32_16x16x32_bf16 v[116:119], v[164:167], v[186:189], v[116:119]
	v_mfma_f32_16x16x32_bf16 v[112:115], v[178:181], v[186:189], v[112:115]
	v_mfma_f32_16x16x32_bf16 v[100:103], v[164:167], v[194:197], v[100:103]
	v_mfma_f32_16x16x32_bf16 v[96:99], v[178:181], v[194:197], v[96:99]
	v_mfma_f32_16x16x32_bf16 v[84:87], v[164:167], v[202:205], v[84:87]
	v_mfma_f32_16x16x32_bf16 v[80:83], v[178:181], v[202:205], v[80:83]
	v_mfma_f32_16x16x32_bf16 v[68:71], v[164:167], v[210:213], v[68:71]
	v_mfma_f32_16x16x32_bf16 v[64:67], v[178:181], v[210:213], v[64:67]
	s_setprio 0
	s_barrier
	s_add_i32 s79, s79, s57
	v_lshl_add_u64 v[168:169], s[42:43], 0, v[134:135]
	s_mov_b32 m0, s79
	ds_read_b128 v[182:185], v173 offset:16384
	ds_read_b128 v[186:189], v173 offset:17408
	ds_read_b128 v[190:193], v173 offset:18432
	ds_read_b128 v[194:197], v173 offset:19456
	ds_read_b128 v[198:201], v173 offset:20480
	ds_read_b128 v[202:205], v173 offset:21504
	ds_read_b128 v[206:209], v173 offset:22528
	ds_read_b128 v[210:213], v173 offset:23552
	global_load_lds_dwordx4 v[168:169], off
	s_add_i32 m0, s79, 0x2000
	s_add_u32 s80, s42, 0x40000
	v_lshl_add_u64 v[214:215], s[42:43], 0, v[138:139]
	s_addc_u32 s81, s43, 0
	s_add_i32 s79, s82, s57
	global_load_lds_dwordx4 v[214:215], off
	v_lshl_add_u64 v[216:217], s[80:81], 0, v[134:135]
	s_mov_b32 m0, s79
	v_lshl_add_u64 v[218:219], s[52:53], 0, v[136:137]
	global_load_lds_dwordx4 v[216:217], off
	v_lshl_add_u64 v[216:217], s[80:81], 0, v[138:139]
	s_add_i32 m0, s79, 0x2000
	s_nop 0
	global_load_lds_dwordx4 v[216:217], off
	v_lshl_add_u64 v[216:217], s[52:53], 0, v[132:133]
	s_mov_b32 m0, s58
	s_nop 0
	global_load_lds_dwordx4 v[216:217], off
	s_mov_b32 m0, s59
	s_nop 0
	global_load_lds_dwordx4 v[218:219], off
	s_waitcnt vmcnt(8)
	s_waitcnt lgkmcnt(0)
	s_barrier
	s_setprio 1
	s_waitcnt lgkmcnt(0)
	v_mfma_f32_16x16x32_bf16 v[60:63], v[128:131], v[182:185], v[60:63]
	v_mfma_f32_16x16x32_bf16 v[56:59], v[150:153], v[182:185], v[56:59]
	v_mfma_f32_16x16x32_bf16 v[44:47], v[128:131], v[190:193], v[44:47]
	v_mfma_f32_16x16x32_bf16 v[40:43], v[150:153], v[190:193], v[40:43]
	v_mfma_f32_16x16x32_bf16 v[28:31], v[128:131], v[198:201], v[28:31]
	v_mfma_f32_16x16x32_bf16 v[24:27], v[150:153], v[198:201], v[24:27]
	v_mfma_f32_16x16x32_bf16 v[12:15], v[128:131], v[206:209], v[12:15]
	v_mfma_f32_16x16x32_bf16 v[8:11], v[150:153], v[206:209], v[8:11]
	v_mfma_f32_16x16x32_bf16 v[60:63], v[146:149], v[186:189], v[60:63]
	v_mfma_f32_16x16x32_bf16 v[56:59], v[154:157], v[186:189], v[56:59]
	v_mfma_f32_16x16x32_bf16 v[44:47], v[146:149], v[194:197], v[44:47]
	v_mfma_f32_16x16x32_bf16 v[40:43], v[154:157], v[194:197], v[40:43]
	v_mfma_f32_16x16x32_bf16 v[28:31], v[146:149], v[202:205], v[28:31]
	v_mfma_f32_16x16x32_bf16 v[24:27], v[154:157], v[202:205], v[24:27]
	v_mfma_f32_16x16x32_bf16 v[12:15], v[146:149], v[210:213], v[12:15]
	v_mfma_f32_16x16x32_bf16 v[8:11], v[154:157], v[210:213], v[8:11]
	v_mfma_f32_16x16x32_bf16 v[52:55], v[160:163], v[182:185], v[52:55]
	v_mfma_f32_16x16x32_bf16 v[48:51], v[174:177], v[182:185], v[48:51]
	v_mfma_f32_16x16x32_bf16 v[36:39], v[160:163], v[190:193], v[36:39]
	v_mfma_f32_16x16x32_bf16 v[32:35], v[174:177], v[190:193], v[32:35]
	v_mfma_f32_16x16x32_bf16 v[20:23], v[160:163], v[198:201], v[20:23]
	v_mfma_f32_16x16x32_bf16 v[16:19], v[174:177], v[198:201], v[16:19]
	v_mfma_f32_16x16x32_bf16 v[4:7], v[160:163], v[206:209], v[4:7]
	v_mfma_f32_16x16x32_bf16 v[0:3], v[174:177], v[206:209], v[0:3]
	v_mfma_f32_16x16x32_bf16 v[52:55], v[164:167], v[186:189], v[52:55]
	v_mfma_f32_16x16x32_bf16 v[48:51], v[178:181], v[186:189], v[48:51]
	v_mfma_f32_16x16x32_bf16 v[36:39], v[164:167], v[194:197], v[36:39]
	v_mfma_f32_16x16x32_bf16 v[32:35], v[178:181], v[194:197], v[32:35]
	v_mfma_f32_16x16x32_bf16 v[20:23], v[164:167], v[202:205], v[20:23]
	v_mfma_f32_16x16x32_bf16 v[16:19], v[178:181], v[202:205], v[16:19]
	v_mfma_f32_16x16x32_bf16 v[4:7], v[164:167], v[210:213], v[4:7]
	v_mfma_f32_16x16x32_bf16 v[0:3], v[178:181], v[210:213], v[0:3]
	s_setprio 0
	s_barrier
	s_add_i32 s79, 0, 0x18000
	v_add_u32_e32 v144, s79, v172
	s_add_i32 s80, 0, 0x1c000
	ds_read_b128 v[128:131], v144
	ds_read_b128 v[146:149], v144 offset:1024
	ds_read_b128 v[150:153], v144 offset:2048
	ds_read_b128 v[154:157], v144 offset:3072
	v_add_u32_e32 v144, s80, v172
	ds_read_b128 v[160:163], v144
	ds_read_b128 v[164:167], v144 offset:1024
	ds_read_b128 v[174:177], v144 offset:2048
	ds_read_b128 v[178:181], v144 offset:3072
	s_add_u32 s52, s52, 0x40000
	s_addc_u32 s53, s53, 0
	s_mov_b32 m0, s60
	v_lshl_add_u64 v[220:221], s[52:53], 0, v[132:133]
	ds_read_b128 v[182:185], v173 offset:32768
	ds_read_b128 v[186:189], v173 offset:33792
	ds_read_b128 v[190:193], v173 offset:34816
	ds_read_b128 v[194:197], v173 offset:35840
	ds_read_b128 v[198:201], v173 offset:36864
	ds_read_b128 v[202:205], v173 offset:37888
	ds_read_b128 v[206:209], v173 offset:38912
	ds_read_b128 v[210:213], v173 offset:39936
	global_load_lds_dwordx4 v[220:221], off
	v_lshl_add_u64 v[220:221], s[52:53], 0, v[136:137]
	s_mov_b32 m0, s61
	s_nop 0
	global_load_lds_dwordx4 v[220:221], off
	s_waitcnt vmcnt(8)
	s_waitcnt lgkmcnt(0)
	s_barrier
	s_setprio 1
	s_waitcnt lgkmcnt(0)
	v_mfma_f32_16x16x32_bf16 v[124:127], v[128:131], v[182:185], v[124:127]
	v_mfma_f32_16x16x32_bf16 v[120:123], v[150:153], v[182:185], v[120:123]
	v_mfma_f32_16x16x32_bf16 v[108:111], v[128:131], v[190:193], v[108:111]
	v_mfma_f32_16x16x32_bf16 v[104:107], v[150:153], v[190:193], v[104:107]
	v_mfma_f32_16x16x32_bf16 v[92:95], v[128:131], v[198:201], v[92:95]
	v_mfma_f32_16x16x32_bf16 v[88:91], v[150:153], v[198:201], v[88:91]
	v_mfma_f32_16x16x32_bf16 v[76:79], v[128:131], v[206:209], v[76:79]
	v_mfma_f32_16x16x32_bf16 v[72:75], v[150:153], v[206:209], v[72:75]
	v_mfma_f32_16x16x32_bf16 v[124:127], v[146:149], v[186:189], v[124:127]
	v_mfma_f32_16x16x32_bf16 v[120:123], v[154:157], v[186:189], v[120:123]
	v_mfma_f32_16x16x32_bf16 v[108:111], v[146:149], v[194:197], v[108:111]
	v_mfma_f32_16x16x32_bf16 v[104:107], v[154:157], v[194:197], v[104:107]
	v_mfma_f32_16x16x32_bf16 v[92:95], v[146:149], v[202:205], v[92:95]
	v_mfma_f32_16x16x32_bf16 v[88:91], v[154:157], v[202:205], v[88:91]
	v_mfma_f32_16x16x32_bf16 v[76:79], v[146:149], v[210:213], v[76:79]
	v_mfma_f32_16x16x32_bf16 v[72:75], v[154:157], v[210:213], v[72:75]
	v_mfma_f32_16x16x32_bf16 v[116:119], v[160:163], v[182:185], v[116:119]
	v_mfma_f32_16x16x32_bf16 v[112:115], v[174:177], v[182:185], v[112:115]
	v_mfma_f32_16x16x32_bf16 v[100:103], v[160:163], v[190:193], v[100:103]
	v_mfma_f32_16x16x32_bf16 v[96:99], v[174:177], v[190:193], v[96:99]
	v_mfma_f32_16x16x32_bf16 v[84:87], v[160:163], v[198:201], v[84:87]
	v_mfma_f32_16x16x32_bf16 v[80:83], v[174:177], v[198:201], v[80:83]
	v_mfma_f32_16x16x32_bf16 v[68:71], v[160:163], v[206:209], v[68:71]
	v_mfma_f32_16x16x32_bf16 v[64:67], v[174:177], v[206:209], v[64:67]
	v_mfma_f32_16x16x32_bf16 v[116:119], v[164:167], v[186:189], v[116:119]
	v_mfma_f32_16x16x32_bf16 v[112:115], v[178:181], v[186:189], v[112:115]
	v_mfma_f32_16x16x32_bf16 v[100:103], v[164:167], v[194:197], v[100:103]
	v_mfma_f32_16x16x32_bf16 v[96:99], v[178:181], v[194:197], v[96:99]
	v_mfma_f32_16x16x32_bf16 v[84:87], v[164:167], v[202:205], v[84:87]
	v_mfma_f32_16x16x32_bf16 v[80:83], v[178:181], v[202:205], v[80:83]
	v_mfma_f32_16x16x32_bf16 v[68:71], v[164:167], v[210:213], v[68:71]
	v_mfma_f32_16x16x32_bf16 v[64:67], v[178:181], v[210:213], v[64:67]
	s_setprio 0
	s_barrier
	s_add_i32 s52, s79, s57
	v_lshl_add_u64 v[168:169], v[168:169], 0, s[20:21]
	s_mov_b32 m0, s52
	ds_read_b128 v[182:185], v173 offset:49152
	ds_read_b128 v[186:189], v173 offset:50176
	ds_read_b128 v[190:193], v173 offset:51200
	ds_read_b128 v[194:197], v173 offset:52224
	ds_read_b128 v[198:201], v173 offset:53248
	ds_read_b128 v[202:205], v173 offset:54272
	ds_read_b128 v[206:209], v173 offset:55296
	ds_read_b128 v[210:213], v173 offset:56320
	global_load_lds_dwordx4 v[168:169], off
	s_add_i32 m0, s52, 0x2000
	s_add_u32 s42, s42, 0x40080
	v_lshl_add_u64 v[168:169], v[214:215], 0, s[20:21]
	s_addc_u32 s43, s43, 0
	s_add_i32 s52, s80, s57
	global_load_lds_dwordx4 v[168:169], off
	v_lshl_add_u64 v[168:169], s[42:43], 0, v[134:135]
	s_mov_b32 m0, s52
	s_nop 0
	global_load_lds_dwordx4 v[168:169], off
	v_lshl_add_u64 v[168:169], s[42:43], 0, v[138:139]
	s_add_i32 m0, s52, 0x2000
	s_nop 0
	global_load_lds_dwordx4 v[168:169], off
	v_lshl_add_u64 v[168:169], v[216:217], 0, s[20:21]
	s_mov_b32 m0, s64
	s_nop 0
	global_load_lds_dwordx4 v[168:169], off
	v_lshl_add_u64 v[168:169], v[218:219], 0, s[20:21]
	s_mov_b32 m0, s65
	s_nop 0
	global_load_lds_dwordx4 v[168:169], off
	s_waitcnt vmcnt(8)
	s_waitcnt lgkmcnt(0)
	s_barrier
	s_setprio 1
	s_waitcnt lgkmcnt(0)
	v_mfma_f32_16x16x32_bf16 v[60:63], v[128:131], v[182:185], v[60:63]
	v_mfma_f32_16x16x32_bf16 v[56:59], v[150:153], v[182:185], v[56:59]
	v_mfma_f32_16x16x32_bf16 v[44:47], v[128:131], v[190:193], v[44:47]
	v_mfma_f32_16x16x32_bf16 v[40:43], v[150:153], v[190:193], v[40:43]
	v_mfma_f32_16x16x32_bf16 v[28:31], v[128:131], v[198:201], v[28:31]
	v_mfma_f32_16x16x32_bf16 v[24:27], v[150:153], v[198:201], v[24:27]
	v_mfma_f32_16x16x32_bf16 v[12:15], v[128:131], v[206:209], v[12:15]
	v_mfma_f32_16x16x32_bf16 v[8:11], v[150:153], v[206:209], v[8:11]
	v_mfma_f32_16x16x32_bf16 v[60:63], v[146:149], v[186:189], v[60:63]
	v_mfma_f32_16x16x32_bf16 v[56:59], v[154:157], v[186:189], v[56:59]
	v_mfma_f32_16x16x32_bf16 v[44:47], v[146:149], v[194:197], v[44:47]
	v_mfma_f32_16x16x32_bf16 v[40:43], v[154:157], v[194:197], v[40:43]
	v_mfma_f32_16x16x32_bf16 v[28:31], v[146:149], v[202:205], v[28:31]
	v_mfma_f32_16x16x32_bf16 v[24:27], v[154:157], v[202:205], v[24:27]
	v_mfma_f32_16x16x32_bf16 v[12:15], v[146:149], v[210:213], v[12:15]
	v_mfma_f32_16x16x32_bf16 v[8:11], v[154:157], v[210:213], v[8:11]
	v_mfma_f32_16x16x32_bf16 v[52:55], v[160:163], v[182:185], v[52:55]
	v_mfma_f32_16x16x32_bf16 v[48:51], v[174:177], v[182:185], v[48:51]
	v_mfma_f32_16x16x32_bf16 v[36:39], v[160:163], v[190:193], v[36:39]
	v_mfma_f32_16x16x32_bf16 v[32:35], v[174:177], v[190:193], v[32:35]
	v_mfma_f32_16x16x32_bf16 v[20:23], v[160:163], v[198:201], v[20:23]
	v_mfma_f32_16x16x32_bf16 v[16:19], v[174:177], v[198:201], v[16:19]
	v_mfma_f32_16x16x32_bf16 v[4:7], v[160:163], v[206:209], v[4:7]
	v_mfma_f32_16x16x32_bf16 v[0:3], v[174:177], v[206:209], v[0:3]
	v_mfma_f32_16x16x32_bf16 v[52:55], v[164:167], v[186:189], v[52:55]
	v_mfma_f32_16x16x32_bf16 v[48:51], v[178:181], v[186:189], v[48:51]
	v_mfma_f32_16x16x32_bf16 v[36:39], v[164:167], v[194:197], v[36:39]
	v_mfma_f32_16x16x32_bf16 v[32:35], v[178:181], v[194:197], v[32:35]
	v_mfma_f32_16x16x32_bf16 v[20:23], v[164:167], v[202:205], v[20:23]
	v_mfma_f32_16x16x32_bf16 v[16:19], v[178:181], v[202:205], v[16:19]
	v_mfma_f32_16x16x32_bf16 v[4:7], v[164:167], v[210:213], v[4:7]
	v_mfma_f32_16x16x32_bf16 v[0:3], v[178:181], v[210:213], v[0:3]
	s_setprio 0
	s_barrier
	s_add_i32 s78, s78, 2
	s_add_u32 s40, s40, 0x100
	s_addc_u32 s41, s41, 0
	s_add_u32 s45, s45, 0x100
	s_addc_u32 s47, s47, 0
	s_cmp_gt_u32 s78, 13
	s_cbranch_scc0 .LBB0_486
	s_and_b64 vcc, exec, s[24:25]
	s_cbranch_vccz .LBB0_489
	s_barrier

.LBB0_625:
	s_add_u32 s50, s40, 0xfffc0080
	s_addc_u32 s51, s41, -1
	s_add_i32 s70, 0, 0x10000
	s_cmp_eq_u32 s69, 12
	s_cselect_b32 s53, s4, s51
	s_cselect_b32 s52, s5, s50
	s_cselect_b32 s51, s39, s68
	s_cselect_b32 s50, s43, s45
	s_add_i32 s72, 0, 0x14000
	v_add_u32_e32 v44, s70, v177
	v_add_u32_e32 v170, s72, v177
	ds_read_b128 v[32:35], v44
	ds_read_b128 v[36:39], v44 offset:1024
	ds_read_b128 v[40:43], v44 offset:2048
	ds_read_b128 v[44:47], v44 offset:3072
	ds_read_b128 v[146:149], v170
	ds_read_b128 v[150:153], v170 offset:1024
	ds_read_b128 v[154:157], v170 offset:2048
	ds_read_b128 v[170:173], v170 offset:3072
	v_lshl_add_u64 v[174:175], s[40:41], 0, v[166:167]
	s_add_i32 m0, s54, 0xc000
	ds_read_b128 v[180:183], v178
	ds_read_b128 v[184:187], v178 offset:1024
	ds_read_b128 v[188:191], v178 offset:2048
	ds_read_b128 v[192:195], v178 offset:3072
	ds_read_b128 v[196:199], v178 offset:4096
	ds_read_b128 v[200:203], v178 offset:5120
	ds_read_b128 v[204:207], v178 offset:6144
	ds_read_b128 v[208:211], v178 offset:7168
	global_load_lds_dwordx4 v[174:175], off
	v_lshl_add_u64 v[174:175], s[40:41], 0, v[168:169]
	s_add_i32 m0, s54, 0xe000
	s_nop 0
	global_load_lds_dwordx4 v[174:175], off
	s_waitcnt vmcnt(8)
	s_waitcnt lgkmcnt(0)
	s_barrier
	s_setprio 1
	s_waitcnt lgkmcnt(0)
	v_mfma_f32_16x16x32_bf16 v[140:143], v[32:35], v[180:183], v[140:143]
	v_mfma_f32_16x16x32_bf16 v[136:139], v[40:43], v[180:183], v[136:139]
	v_mfma_f32_16x16x32_bf16 v[124:127], v[32:35], v[188:191], v[124:127]
	v_mfma_f32_16x16x32_bf16 v[120:123], v[40:43], v[188:191], v[120:123]
	v_mfma_f32_16x16x32_bf16 v[108:111], v[32:35], v[196:199], v[108:111]
	v_mfma_f32_16x16x32_bf16 v[104:107], v[40:43], v[196:199], v[104:107]
	v_mfma_f32_16x16x32_bf16 v[92:95], v[32:35], v[204:207], v[92:95]
	v_mfma_f32_16x16x32_bf16 v[88:91], v[40:43], v[204:207], v[88:91]
	v_mfma_f32_16x16x32_bf16 v[140:143], v[36:39], v[184:187], v[140:143]
	v_mfma_f32_16x16x32_bf16 v[136:139], v[44:47], v[184:187], v[136:139]
	v_mfma_f32_16x16x32_bf16 v[124:127], v[36:39], v[192:195], v[124:127]
	v_mfma_f32_16x16x32_bf16 v[120:123], v[44:47], v[192:195], v[120:123]
	v_mfma_f32_16x16x32_bf16 v[108:111], v[36:39], v[200:203], v[108:111]
	v_mfma_f32_16x16x32_bf16 v[104:107], v[44:47], v[200:203], v[104:107]
	v_mfma_f32_16x16x32_bf16 v[92:95], v[36:39], v[208:211], v[92:95]
	v_mfma_f32_16x16x32_bf16 v[88:91], v[44:47], v[208:211], v[88:91]
	v_mfma_f32_16x16x32_bf16 v[132:135], v[146:149], v[180:183], v[132:135]
	v_mfma_f32_16x16x32_bf16 v[128:131], v[154:157], v[180:183], v[128:131]
	v_mfma_f32_16x16x32_bf16 v[116:119], v[146:149], v[188:191], v[116:119]
	v_mfma_f32_16x16x32_bf16 v[112:115], v[154:157], v[188:191], v[112:115]
	v_mfma_f32_16x16x32_bf16 v[100:103], v[146:149], v[196:199], v[100:103]
	v_mfma_f32_16x16x32_bf16 v[96:99], v[154:157], v[196:199], v[96:99]
	v_mfma_f32_16x16x32_bf16 v[84:87], v[146:149], v[204:207], v[84:87]
	v_mfma_f32_16x16x32_bf16 v[80:83], v[154:157], v[204:207], v[80:83]
	v_mfma_f32_16x16x32_bf16 v[132:135], v[150:153], v[184:187], v[132:135]
	v_mfma_f32_16x16x32_bf16 v[128:131], v[170:173], v[184:187], v[128:131]
	v_mfma_f32_16x16x32_bf16 v[116:119], v[150:153], v[192:195], v[116:119]
	v_mfma_f32_16x16x32_bf16 v[112:115], v[170:173], v[192:195], v[112:115]
	v_mfma_f32_16x16x32_bf16 v[100:103], v[150:153], v[200:203], v[100:103]
	v_mfma_f32_16x16x32_bf16 v[96:99], v[170:173], v[200:203], v[96:99]
	v_mfma_f32_16x16x32_bf16 v[84:87], v[150:153], v[208:211], v[84:87]
	v_mfma_f32_16x16x32_bf16 v[80:83], v[170:173], v[208:211], v[80:83]
	s_setprio 0
	s_barrier
	s_add_i32 s70, s70, s27
	v_lshl_add_u64 v[174:175], s[50:51], 0, v[144:145]
	s_mov_b32 m0, s70
	ds_read_b128 v[180:183], v178 offset:16384
	ds_read_b128 v[184:187], v178 offset:17408
	ds_read_b128 v[188:191], v178 offset:18432
	ds_read_b128 v[192:195], v178 offset:19456
	ds_read_b128 v[196:199], v178 offset:20480
	ds_read_b128 v[200:203], v178 offset:21504
	ds_read_b128 v[204:207], v178 offset:22528
	ds_read_b128 v[208:211], v178 offset:23552
	global_load_lds_dwordx4 v[174:175], off
	s_add_i32 m0, s70, 0x2000
	s_add_u32 s70, s50, 0x40000
	v_lshl_add_u64 v[212:213], s[50:51], 0, v[164:165]
	s_addc_u32 s71, s51, 0
	s_add_i32 s72, s72, s27
	global_load_lds_dwordx4 v[212:213], off
	v_lshl_add_u64 v[214:215], s[70:71], 0, v[144:145]
	s_mov_b32 m0, s72
	v_lshl_add_u64 v[216:217], s[52:53], 0, v[162:163]
	global_load_lds_dwordx4 v[214:215], off
	v_lshl_add_u64 v[214:215], s[70:71], 0, v[164:165]
	s_add_i32 m0, s72, 0x2000
	s_nop 0
	global_load_lds_dwordx4 v[214:215], off
	v_lshl_add_u64 v[214:215], s[52:53], 0, v[160:161]
	s_mov_b32 m0, s54
	s_nop 0
	global_load_lds_dwordx4 v[214:215], off
	s_mov_b32 m0, s55
	s_nop 0
	global_load_lds_dwordx4 v[216:217], off
	s_waitcnt vmcnt(8)
	s_waitcnt lgkmcnt(0)
	s_barrier
	s_setprio 1
	s_waitcnt lgkmcnt(0)
	v_mfma_f32_16x16x32_bf16 v[76:79], v[32:35], v[180:183], v[76:79]
	v_mfma_f32_16x16x32_bf16 v[72:75], v[40:43], v[180:183], v[72:75]
	v_mfma_f32_16x16x32_bf16 v[60:63], v[32:35], v[188:191], v[60:63]
	v_mfma_f32_16x16x32_bf16 v[56:59], v[40:43], v[188:191], v[56:59]
	v_mfma_f32_16x16x32_bf16 v[28:31], v[32:35], v[196:199], v[28:31]
	v_mfma_f32_16x16x32_bf16 v[24:27], v[40:43], v[196:199], v[24:27]
	v_mfma_f32_16x16x32_bf16 v[12:15], v[32:35], v[204:207], v[12:15]
	v_mfma_f32_16x16x32_bf16 v[8:11], v[40:43], v[204:207], v[8:11]
	v_mfma_f32_16x16x32_bf16 v[76:79], v[36:39], v[184:187], v[76:79]
	v_mfma_f32_16x16x32_bf16 v[72:75], v[44:47], v[184:187], v[72:75]
	v_mfma_f32_16x16x32_bf16 v[60:63], v[36:39], v[192:195], v[60:63]
	v_mfma_f32_16x16x32_bf16 v[56:59], v[44:47], v[192:195], v[56:59]
	v_mfma_f32_16x16x32_bf16 v[28:31], v[36:39], v[200:203], v[28:31]
	v_mfma_f32_16x16x32_bf16 v[24:27], v[44:47], v[200:203], v[24:27]
	v_mfma_f32_16x16x32_bf16 v[12:15], v[36:39], v[208:211], v[12:15]
	v_mfma_f32_16x16x32_bf16 v[8:11], v[44:47], v[208:211], v[8:11]
	v_mfma_f32_16x16x32_bf16 v[20:23], v[146:149], v[196:199], v[20:23]
	v_mfma_f32_16x16x32_bf16 v[16:19], v[154:157], v[196:199], v[16:19]
	v_mfma_f32_16x16x32_bf16 v[4:7], v[146:149], v[204:207], v[4:7]
	v_mfma_f32_16x16x32_bf16 v[0:3], v[154:157], v[204:207], v[0:3]
	v_mfma_f32_16x16x32_bf16 v[32:35], v[146:149], v[180:183], v[68:71]
	v_mfma_f32_16x16x32_bf16 v[36:39], v[154:157], v[180:183], v[64:67]
	v_mfma_f32_16x16x32_bf16 v[40:43], v[146:149], v[188:191], v[52:55]
	v_mfma_f32_16x16x32_bf16 v[44:47], v[154:157], v[188:191], v[48:51]
	v_mfma_f32_16x16x32_bf16 v[20:23], v[150:153], v[200:203], v[20:23]
	v_mfma_f32_16x16x32_bf16 v[16:19], v[170:173], v[200:203], v[16:19]
	v_mfma_f32_16x16x32_bf16 v[4:7], v[150:153], v[208:211], v[4:7]
	v_mfma_f32_16x16x32_bf16 v[0:3], v[170:173], v[208:211], v[0:3]
	v_mfma_f32_16x16x32_bf16 v[32:35], v[150:153], v[184:187], v[32:35]
	v_mfma_f32_16x16x32_bf16 v[36:39], v[170:173], v[184:187], v[36:39]
	v_mfma_f32_16x16x32_bf16 v[40:43], v[150:153], v[192:195], v[40:43]
	v_mfma_f32_16x16x32_bf16 v[44:47], v[170:173], v[192:195], v[44:47]
	s_setprio 0
	s_barrier
	s_add_i32 s70, 0, 0x18000
	s_add_i32 s71, 0, 0x1c000
	v_add_u32_e32 v68, s70, v177
	v_add_u32_e32 v170, s71, v177
	ds_read_b128 v[48:51], v68
	ds_read_b128 v[52:55], v68 offset:1024
	ds_read_b128 v[64:67], v68 offset:2048
	ds_read_b128 v[68:71], v68 offset:3072
	ds_read_b128 v[146:149], v170
	ds_read_b128 v[150:153], v170 offset:1024
	ds_read_b128 v[154:157], v170 offset:2048
	ds_read_b128 v[170:173], v170 offset:3072
	s_add_u32 s52, s52, 0x40000
	s_addc_u32 s53, s53, 0
	s_mov_b32 m0, s56
	v_lshl_add_u64 v[218:219], s[52:53], 0, v[160:161]
	ds_read_b128 v[180:183], v178 offset:32768
	ds_read_b128 v[184:187], v178 offset:33792
	ds_read_b128 v[188:191], v178 offset:34816
	ds_read_b128 v[192:195], v178 offset:35840
	ds_read_b128 v[196:199], v178 offset:36864
	ds_read_b128 v[200:203], v178 offset:37888
	ds_read_b128 v[204:207], v178 offset:38912
	ds_read_b128 v[208:211], v178 offset:39936
	global_load_lds_dwordx4 v[218:219], off
	v_lshl_add_u64 v[218:219], s[52:53], 0, v[162:163]
	s_mov_b32 m0, s57
	s_nop 0
	global_load_lds_dwordx4 v[218:219], off
	s_waitcnt vmcnt(8)
	s_waitcnt lgkmcnt(0)
	s_barrier
	s_setprio 1
	s_waitcnt lgkmcnt(0)
	v_mfma_f32_16x16x32_bf16 v[140:143], v[48:51], v[180:183], v[140:143]
	v_mfma_f32_16x16x32_bf16 v[136:139], v[64:67], v[180:183], v[136:139]
	v_mfma_f32_16x16x32_bf16 v[124:127], v[48:51], v[188:191], v[124:127]
	v_mfma_f32_16x16x32_bf16 v[120:123], v[64:67], v[188:191], v[120:123]
	v_mfma_f32_16x16x32_bf16 v[108:111], v[48:51], v[196:199], v[108:111]
	v_mfma_f32_16x16x32_bf16 v[104:107], v[64:67], v[196:199], v[104:107]
	v_mfma_f32_16x16x32_bf16 v[92:95], v[48:51], v[204:207], v[92:95]
	v_mfma_f32_16x16x32_bf16 v[88:91], v[64:67], v[204:207], v[88:91]
	v_mfma_f32_16x16x32_bf16 v[140:143], v[52:55], v[184:187], v[140:143]
	v_mfma_f32_16x16x32_bf16 v[136:139], v[68:71], v[184:187], v[136:139]
	v_mfma_f32_16x16x32_bf16 v[124:127], v[52:55], v[192:195], v[124:127]
	v_mfma_f32_16x16x32_bf16 v[120:123], v[68:71], v[192:195], v[120:123]
	v_mfma_f32_16x16x32_bf16 v[108:111], v[52:55], v[200:203], v[108:111]
	v_mfma_f32_16x16x32_bf16 v[104:107], v[68:71], v[200:203], v[104:107]
	v_mfma_f32_16x16x32_bf16 v[92:95], v[52:55], v[208:211], v[92:95]
	v_mfma_f32_16x16x32_bf16 v[88:91], v[68:71], v[208:211], v[88:91]
	v_mfma_f32_16x16x32_bf16 v[132:135], v[146:149], v[180:183], v[132:135]
	v_mfma_f32_16x16x32_bf16 v[128:131], v[154:157], v[180:183], v[128:131]
	v_mfma_f32_16x16x32_bf16 v[116:119], v[146:149], v[188:191], v[116:119]
	v_mfma_f32_16x16x32_bf16 v[112:115], v[154:157], v[188:191], v[112:115]
	v_mfma_f32_16x16x32_bf16 v[100:103], v[146:149], v[196:199], v[100:103]
	v_mfma_f32_16x16x32_bf16 v[96:99], v[154:157], v[196:199], v[96:99]
	v_mfma_f32_16x16x32_bf16 v[84:87], v[146:149], v[204:207], v[84:87]
	v_mfma_f32_16x16x32_bf16 v[80:83], v[154:157], v[204:207], v[80:83]
	v_mfma_f32_16x16x32_bf16 v[132:135], v[150:153], v[184:187], v[132:135]
	v_mfma_f32_16x16x32_bf16 v[128:131], v[170:173], v[184:187], v[128:131]
	v_mfma_f32_16x16x32_bf16 v[116:119], v[150:153], v[192:195], v[116:119]
	v_mfma_f32_16x16x32_bf16 v[112:115], v[170:173], v[192:195], v[112:115]
	v_mfma_f32_16x16x32_bf16 v[100:103], v[150:153], v[200:203], v[100:103]
	v_mfma_f32_16x16x32_bf16 v[96:99], v[170:173], v[200:203], v[96:99]
	v_mfma_f32_16x16x32_bf16 v[84:87], v[150:153], v[208:211], v[84:87]
	v_mfma_f32_16x16x32_bf16 v[80:83], v[170:173], v[208:211], v[80:83]
	s_setprio 0
	s_barrier
	s_add_i32 s52, s70, s27
	v_lshl_add_u64 v[174:175], v[174:175], 0, s[20:21]
	s_mov_b32 m0, s52
	ds_read_b128 v[180:183], v178 offset:49152
	ds_read_b128 v[184:187], v178 offset:50176
	ds_read_b128 v[188:191], v178 offset:51200
	ds_read_b128 v[192:195], v178 offset:52224
	ds_read_b128 v[196:199], v178 offset:53248
	ds_read_b128 v[200:203], v178 offset:54272
	ds_read_b128 v[204:207], v178 offset:55296
	ds_read_b128 v[208:211], v178 offset:56320
	global_load_lds_dwordx4 v[174:175], off
	s_add_i32 m0, s52, 0x2000
	s_add_u32 s50, s50, 0x40080
	v_lshl_add_u64 v[174:175], v[212:213], 0, s[20:21]
	s_addc_u32 s51, s51, 0
	s_add_i32 s52, s71, s27
	global_load_lds_dwordx4 v[174:175], off
	v_lshl_add_u64 v[174:175], s[50:51], 0, v[144:145]
	s_mov_b32 m0, s52
	s_nop 0
	global_load_lds_dwordx4 v[174:175], off
	v_lshl_add_u64 v[174:175], s[50:51], 0, v[164:165]
	s_add_i32 m0, s52, 0x2000
	s_nop 0
	global_load_lds_dwordx4 v[174:175], off
	v_lshl_add_u64 v[174:175], v[214:215], 0, s[20:21]
	s_mov_b32 m0, s60
	s_nop 0
	global_load_lds_dwordx4 v[174:175], off
	v_lshl_add_u64 v[174:175], v[216:217], 0, s[20:21]
	s_mov_b32 m0, s61
	s_nop 0
	global_load_lds_dwordx4 v[174:175], off
	s_waitcnt vmcnt(8)
	s_waitcnt lgkmcnt(0)
	s_barrier
	s_setprio 1
	s_waitcnt lgkmcnt(0)
	v_mfma_f32_16x16x32_bf16 v[76:79], v[48:51], v[180:183], v[76:79]
	v_mfma_f32_16x16x32_bf16 v[72:75], v[64:67], v[180:183], v[72:75]
	v_mfma_f32_16x16x32_bf16 v[60:63], v[48:51], v[188:191], v[60:63]
	v_mfma_f32_16x16x32_bf16 v[56:59], v[64:67], v[188:191], v[56:59]
	v_mfma_f32_16x16x32_bf16 v[28:31], v[48:51], v[196:199], v[28:31]
	v_mfma_f32_16x16x32_bf16 v[24:27], v[64:67], v[196:199], v[24:27]
	v_mfma_f32_16x16x32_bf16 v[12:15], v[48:51], v[204:207], v[12:15]
	v_mfma_f32_16x16x32_bf16 v[8:11], v[64:67], v[204:207], v[8:11]
	v_mfma_f32_16x16x32_bf16 v[76:79], v[52:55], v[184:187], v[76:79]
	v_mfma_f32_16x16x32_bf16 v[72:75], v[68:71], v[184:187], v[72:75]
	v_mfma_f32_16x16x32_bf16 v[60:63], v[52:55], v[192:195], v[60:63]
	v_mfma_f32_16x16x32_bf16 v[56:59], v[68:71], v[192:195], v[56:59]
	v_mfma_f32_16x16x32_bf16 v[28:31], v[52:55], v[200:203], v[28:31]
	v_mfma_f32_16x16x32_bf16 v[24:27], v[68:71], v[200:203], v[24:27]
	v_mfma_f32_16x16x32_bf16 v[12:15], v[52:55], v[208:211], v[12:15]
	v_mfma_f32_16x16x32_bf16 v[8:11], v[68:71], v[208:211], v[8:11]
	v_mfma_f32_16x16x32_bf16 v[32:35], v[146:149], v[180:183], v[32:35]
	v_mfma_f32_16x16x32_bf16 v[68:71], v[150:153], v[184:187], v[32:35]
	v_mfma_f32_16x16x32_bf16 v[32:35], v[154:157], v[180:183], v[36:39]
	v_mfma_f32_16x16x32_bf16 v[64:67], v[170:173], v[184:187], v[32:35]
	v_mfma_f32_16x16x32_bf16 v[32:35], v[146:149], v[188:191], v[40:43]
	v_mfma_f32_16x16x32_bf16 v[52:55], v[150:153], v[192:195], v[32:35]
	v_mfma_f32_16x16x32_bf16 v[32:35], v[154:157], v[188:191], v[44:47]
	v_mfma_f32_16x16x32_bf16 v[20:23], v[146:149], v[196:199], v[20:23]
	v_mfma_f32_16x16x32_bf16 v[16:19], v[154:157], v[196:199], v[16:19]
	v_mfma_f32_16x16x32_bf16 v[4:7], v[146:149], v[204:207], v[4:7]
	v_mfma_f32_16x16x32_bf16 v[0:3], v[154:157], v[204:207], v[0:3]
	v_mfma_f32_16x16x32_bf16 v[48:51], v[170:173], v[192:195], v[32:35]
	v_mfma_f32_16x16x32_bf16 v[20:23], v[150:153], v[200:203], v[20:23]
	v_mfma_f32_16x16x32_bf16 v[16:19], v[170:173], v[200:203], v[16:19]
	v_mfma_f32_16x16x32_bf16 v[4:7], v[150:153], v[208:211], v[4:7]
	v_mfma_f32_16x16x32_bf16 v[0:3], v[170:173], v[208:211], v[0:3]
	s_setprio 0
	s_barrier
	s_add_i32 s69, s69, 2
	s_add_u32 s40, s40, 0x100
	s_addc_u32 s41, s41, 0
	s_add_u32 s45, s45, 0x100
	s_addc_u32 s68, s68, 0
	s_cmp_gt_u32 s69, 13
	s_cbranch_scc0 .LBB0_625
	s_and_b64 vcc, exec, s[24:25]
	s_cbranch_vccz .LBB0_628
	s_barrier

.LBB0_737:
	s_ashr_i32 s25, s24, 31
	s_lshl_b64 s[42:43], s[24:25], 17
	s_add_u32 s42, s15, s42
	s_addc_u32 s43, s26, s43
	s_and_b64 s[44:45], s[36:37], exec
	s_cselect_b32 s53, s43, s47
	s_cselect_b32 s52, s42, s46
	s_ashr_i32 s39, s38, 31
	s_lshl_b64 s[44:45], s[38:39], 17
	s_add_u32 s44, s27, s44
	s_addc_u32 s45, s30, s45
	s_and_b64 s[48:49], s[36:37], exec
	s_cselect_b32 s49, s45, s51
	s_cselect_b32 s48, s44, s50
	s_add_i32 s25, 0, 0x10000
	s_add_i32 s39, 0, 0x14000
	v_add_u32_e32 v154, s25, v136
	v_add_u32_e32 v155, s39, v136
	ds_read_b128 v[0:3], v154
	ds_read_b128 v[4:7], v154 offset:1024
	ds_read_b128 v[8:11], v154 offset:2048
	ds_read_b128 v[12:15], v154 offset:3072
	ds_read_b128 v[16:19], v155
	ds_read_b128 v[20:23], v155 offset:1024
	ds_read_b128 v[24:27], v155 offset:2048
	ds_read_b128 v[28:31], v155 offset:3072
	s_add_u32 s64, s46, 0x10080
	s_addc_u32 s65, s47, 0
	s_add_i32 s69, s41, 0xc000
	v_lshl_add_u64 v[64:65], s[64:65], 0, v[132:133]
	s_mov_b32 m0, s69
	s_add_i32 s5, s41, 0xe000
	ds_read_b128 v[32:35], v137
	ds_read_b128 v[36:39], v137 offset:1024
	ds_read_b128 v[40:43], v137 offset:2048
	ds_read_b128 v[44:47], v137 offset:3072
	ds_read_b128 v[48:51], v137 offset:4096
	ds_read_b128 v[52:55], v137 offset:5120
	ds_read_b128 v[56:59], v137 offset:6144
	ds_read_b128 v[60:63], v137 offset:7168
	global_load_lds_dwordx4 v[64:65], off
	v_lshl_add_u64 v[64:65], s[64:65], 0, v[130:131]
	s_mov_b32 m0, s5
	s_nop 0
	global_load_lds_dwordx4 v[64:65], off
	s_waitcnt vmcnt(8)
	s_waitcnt lgkmcnt(0)
	s_barrier
	s_setprio 1
	s_waitcnt lgkmcnt(0)
	v_mfma_f32_16x16x32_bf16 v[64:67], v[0:3], v[32:35], 0
	v_mfma_f32_16x16x32_bf16 v[68:71], v[8:11], v[32:35], 0
	v_mfma_f32_16x16x32_bf16 v[72:75], v[0:3], v[40:43], 0
	v_mfma_f32_16x16x32_bf16 v[76:79], v[8:11], v[40:43], 0
	v_mfma_f32_16x16x32_bf16 v[80:83], v[0:3], v[48:51], 0
	v_mfma_f32_16x16x32_bf16 v[84:87], v[8:11], v[48:51], 0
	v_mfma_f32_16x16x32_bf16 v[88:91], v[0:3], v[56:59], 0
	v_mfma_f32_16x16x32_bf16 v[92:95], v[8:11], v[56:59], 0
	v_mfma_f32_16x16x32_bf16 v[64:67], v[4:7], v[36:39], v[64:67]
	v_mfma_f32_16x16x32_bf16 v[68:71], v[12:15], v[36:39], v[68:71]
	v_mfma_f32_16x16x32_bf16 v[72:75], v[4:7], v[44:47], v[72:75]
	v_mfma_f32_16x16x32_bf16 v[76:79], v[12:15], v[44:47], v[76:79]
	v_mfma_f32_16x16x32_bf16 v[80:83], v[4:7], v[52:55], v[80:83]
	v_mfma_f32_16x16x32_bf16 v[84:87], v[12:15], v[52:55], v[84:87]
	v_mfma_f32_16x16x32_bf16 v[88:91], v[4:7], v[60:63], v[88:91]
	v_mfma_f32_16x16x32_bf16 v[92:95], v[12:15], v[60:63], v[92:95]
	v_mfma_f32_16x16x32_bf16 v[96:99], v[16:19], v[32:35], 0
	v_mfma_f32_16x16x32_bf16 v[32:35], v[24:27], v[32:35], 0
	v_mfma_f32_16x16x32_bf16 v[96:99], v[20:23], v[36:39], v[96:99]
	v_mfma_f32_16x16x32_bf16 v[32:35], v[28:31], v[36:39], v[32:35]
	v_mfma_f32_16x16x32_bf16 v[36:39], v[16:19], v[40:43], 0
	v_mfma_f32_16x16x32_bf16 v[40:43], v[24:27], v[40:43], 0
	v_mfma_f32_16x16x32_bf16 v[36:39], v[20:23], v[44:47], v[36:39]
	v_mfma_f32_16x16x32_bf16 v[40:43], v[28:31], v[44:47], v[40:43]
	v_mfma_f32_16x16x32_bf16 v[44:47], v[16:19], v[48:51], 0
	v_mfma_f32_16x16x32_bf16 v[48:51], v[24:27], v[48:51], 0
	v_mfma_f32_16x16x32_bf16 v[44:47], v[20:23], v[52:55], v[44:47]
	v_mfma_f32_16x16x32_bf16 v[48:51], v[28:31], v[52:55], v[48:51]
	v_mfma_f32_16x16x32_bf16 v[52:55], v[16:19], v[56:59], 0
	v_mfma_f32_16x16x32_bf16 v[56:59], v[24:27], v[56:59], 0
	v_mfma_f32_16x16x32_bf16 v[52:55], v[20:23], v[60:63], v[52:55]
	v_mfma_f32_16x16x32_bf16 v[56:59], v[28:31], v[60:63], v[56:59]
	s_setprio 0
	s_barrier
	s_add_i32 s65, s25, s54
	v_lshl_add_u64 v[142:143], s[50:51], 0, v[144:145]
	s_mov_b64 s[72:73], 0x100
	s_add_i32 s25, s65, 0x2000
	v_lshl_add_u64 v[138:139], v[142:143], 0, s[72:73]
	s_mov_b32 m0, s65
	v_lshl_add_u64 v[146:147], s[50:51], 0, v[128:129]
	s_add_u32 s70, s50, 0x10100
	ds_read_b128 v[60:63], v137 offset:16384
	ds_read_b128 v[100:103], v137 offset:17408
	ds_read_b128 v[104:107], v137 offset:18432
	ds_read_b128 v[108:111], v137 offset:19456
	ds_read_b128 v[112:115], v137 offset:20480
	ds_read_b128 v[116:119], v137 offset:21504
	ds_read_b128 v[120:123], v137 offset:22528
	ds_read_b128 v[124:127], v137 offset:23552
	global_load_lds_dwordx4 v[138:139], off
	v_lshl_add_u64 v[138:139], v[146:147], 0, s[72:73]
	s_mov_b32 m0, s25
	s_addc_u32 s71, s51, 0
	s_add_i32 s39, s39, s54
	global_load_lds_dwordx4 v[138:139], off
	v_lshl_add_u64 v[138:139], s[70:71], 0, v[144:145]
	s_mov_b32 m0, s39
	s_add_i32 s64, s39, 0x2000
	global_load_lds_dwordx4 v[138:139], off
	v_lshl_add_u64 v[138:139], s[70:71], 0, v[128:129]
	s_mov_b32 m0, s64
	v_lshl_add_u64 v[148:149], s[46:47], 0, v[132:133]
	global_load_lds_dwordx4 v[138:139], off
	v_lshl_add_u64 v[138:139], v[148:149], 0, s[72:73]
	s_mov_b32 m0, s41
	v_lshl_add_u64 v[150:151], s[46:47], 0, v[130:131]
	global_load_lds_dwordx4 v[138:139], off
	v_lshl_add_u64 v[138:139], v[150:151], 0, s[72:73]
	s_mov_b32 m0, s55
	s_nop 0
	global_load_lds_dwordx4 v[138:139], off
	s_waitcnt vmcnt(8)
	s_waitcnt lgkmcnt(0)
	s_barrier
	s_setprio 1
	s_waitcnt lgkmcnt(0)
	v_mfma_f32_16x16x32_bf16 v[138:141], v[0:3], v[60:63], 0
	v_mfma_f32_16x16x32_bf16 v[164:167], v[0:3], v[104:107], 0
	v_mfma_f32_16x16x32_bf16 v[172:175], v[0:3], v[112:115], 0
	v_mfma_f32_16x16x32_bf16 v[0:3], v[0:3], v[120:123], 0
	v_mfma_f32_16x16x32_bf16 v[138:141], v[4:7], v[100:103], v[138:141]
	v_mfma_f32_16x16x32_bf16 v[164:167], v[4:7], v[108:111], v[164:167]
	v_mfma_f32_16x16x32_bf16 v[172:175], v[4:7], v[116:119], v[172:175]
	v_mfma_f32_16x16x32_bf16 v[0:3], v[4:7], v[124:127], v[0:3]
	v_mfma_f32_16x16x32_bf16 v[4:7], v[8:11], v[120:123], 0
	v_mfma_f32_16x16x32_bf16 v[160:163], v[8:11], v[60:63], 0
	v_mfma_f32_16x16x32_bf16 v[168:171], v[8:11], v[104:107], 0
	v_mfma_f32_16x16x32_bf16 v[176:179], v[8:11], v[112:115], 0
	v_mfma_f32_16x16x32_bf16 v[4:7], v[12:15], v[124:127], v[4:7]
	v_mfma_f32_16x16x32_bf16 v[160:163], v[12:15], v[100:103], v[160:163]
	v_mfma_f32_16x16x32_bf16 v[168:171], v[12:15], v[108:111], v[168:171]
	v_mfma_f32_16x16x32_bf16 v[176:179], v[12:15], v[116:119], v[176:179]
	v_mfma_f32_16x16x32_bf16 v[8:11], v[16:19], v[60:63], 0
	v_mfma_f32_16x16x32_bf16 v[12:15], v[24:27], v[60:63], 0
	v_mfma_f32_16x16x32_bf16 v[8:11], v[20:23], v[100:103], v[8:11]
	v_mfma_f32_16x16x32_bf16 v[12:15], v[28:31], v[100:103], v[12:15]
	v_mfma_f32_16x16x32_bf16 v[60:63], v[16:19], v[104:107], 0
	v_mfma_f32_16x16x32_bf16 v[100:103], v[24:27], v[104:107], 0
	v_mfma_f32_16x16x32_bf16 v[104:107], v[16:19], v[112:115], 0
	v_mfma_f32_16x16x32_bf16 v[16:19], v[16:19], v[120:123], 0
	v_mfma_f32_16x16x32_bf16 v[60:63], v[20:23], v[108:111], v[60:63]
	v_mfma_f32_16x16x32_bf16 v[100:103], v[28:31], v[108:111], v[100:103]
	v_mfma_f32_16x16x32_bf16 v[104:107], v[20:23], v[116:119], v[104:107]
	v_mfma_f32_16x16x32_bf16 v[108:111], v[24:27], v[112:115], 0
	v_mfma_f32_16x16x32_bf16 v[16:19], v[20:23], v[124:127], v[16:19]
	v_mfma_f32_16x16x32_bf16 v[20:23], v[24:27], v[120:123], 0
	v_mfma_f32_16x16x32_bf16 v[108:111], v[28:31], v[116:119], v[108:111]
	v_mfma_f32_16x16x32_bf16 v[20:23], v[28:31], v[124:127], v[20:23]
	s_setprio 0
	s_barrier
	s_add_i32 s68, 0, 0x18000
	s_add_i32 s74, 0, 0x1c000
	v_add_u32_e32 v156, s68, v136
	v_add_u32_e32 v157, s74, v136
	ds_read_b128 v[24:27], v156
	ds_read_b128 v[28:31], v156 offset:1024
	ds_read_b128 v[112:115], v156 offset:2048
	ds_read_b128 v[116:119], v156 offset:3072
	ds_read_b128 v[120:123], v157
	ds_read_b128 v[124:127], v157 offset:1024
	ds_read_b128 v[180:183], v157 offset:2048
	ds_read_b128 v[184:187], v157 offset:3072
	s_add_u32 s70, s46, 0x10100
	s_addc_u32 s71, s47, 0
	s_mov_b32 m0, s56
	v_lshl_add_u64 v[152:153], s[70:71], 0, v[132:133]
	ds_read_b128 v[188:191], v137 offset:32768
	ds_read_b128 v[192:195], v137 offset:33792
	ds_read_b128 v[196:199], v137 offset:34816
	ds_read_b128 v[200:203], v137 offset:35840
	ds_read_b128 v[204:207], v137 offset:36864
	ds_read_b128 v[208:211], v137 offset:37888
	ds_read_b128 v[212:215], v137 offset:38912
	ds_read_b128 v[216:219], v137 offset:39936
	global_load_lds_dwordx4 v[152:153], off
	v_lshl_add_u64 v[152:153], s[70:71], 0, v[130:131]
	s_mov_b32 m0, s57
	s_nop 0
	global_load_lds_dwordx4 v[152:153], off
	s_waitcnt vmcnt(8)
	s_waitcnt lgkmcnt(0)
	s_barrier
	s_setprio 1
	s_waitcnt lgkmcnt(0)
	v_mfma_f32_16x16x32_bf16 v[64:67], v[24:27], v[188:191], v[64:67]
	v_mfma_f32_16x16x32_bf16 v[68:71], v[112:115], v[188:191], v[68:71]
	v_mfma_f32_16x16x32_bf16 v[72:75], v[24:27], v[196:199], v[72:75]
	v_mfma_f32_16x16x32_bf16 v[76:79], v[112:115], v[196:199], v[76:79]
	v_mfma_f32_16x16x32_bf16 v[80:83], v[24:27], v[204:207], v[80:83]
	v_mfma_f32_16x16x32_bf16 v[84:87], v[112:115], v[204:207], v[84:87]
	v_mfma_f32_16x16x32_bf16 v[88:91], v[24:27], v[212:215], v[88:91]
	v_mfma_f32_16x16x32_bf16 v[92:95], v[112:115], v[212:215], v[92:95]
	v_mfma_f32_16x16x32_bf16 v[64:67], v[28:31], v[192:195], v[64:67]
	v_mfma_f32_16x16x32_bf16 v[68:71], v[116:119], v[192:195], v[68:71]
	v_mfma_f32_16x16x32_bf16 v[72:75], v[28:31], v[200:203], v[72:75]
	v_mfma_f32_16x16x32_bf16 v[76:79], v[116:119], v[200:203], v[76:79]
	v_mfma_f32_16x16x32_bf16 v[80:83], v[28:31], v[208:211], v[80:83]
	v_mfma_f32_16x16x32_bf16 v[84:87], v[116:119], v[208:211], v[84:87]
	v_mfma_f32_16x16x32_bf16 v[88:91], v[28:31], v[216:219], v[88:91]
	v_mfma_f32_16x16x32_bf16 v[92:95], v[116:119], v[216:219], v[92:95]
	v_mfma_f32_16x16x32_bf16 v[96:99], v[120:123], v[188:191], v[96:99]
	v_mfma_f32_16x16x32_bf16 v[32:35], v[180:183], v[188:191], v[32:35]
	v_mfma_f32_16x16x32_bf16 v[36:39], v[120:123], v[196:199], v[36:39]
	v_mfma_f32_16x16x32_bf16 v[40:43], v[180:183], v[196:199], v[40:43]
	v_mfma_f32_16x16x32_bf16 v[44:47], v[120:123], v[204:207], v[44:47]
	v_mfma_f32_16x16x32_bf16 v[48:51], v[180:183], v[204:207], v[48:51]
	v_mfma_f32_16x16x32_bf16 v[52:55], v[120:123], v[212:215], v[52:55]
	v_mfma_f32_16x16x32_bf16 v[56:59], v[180:183], v[212:215], v[56:59]
	v_mfma_f32_16x16x32_bf16 v[96:99], v[124:127], v[192:195], v[96:99]
	v_mfma_f32_16x16x32_bf16 v[32:35], v[184:187], v[192:195], v[32:35]
	v_mfma_f32_16x16x32_bf16 v[36:39], v[124:127], v[200:203], v[36:39]
	v_mfma_f32_16x16x32_bf16 v[40:43], v[184:187], v[200:203], v[40:43]
	v_mfma_f32_16x16x32_bf16 v[44:47], v[124:127], v[208:211], v[44:47]
	v_mfma_f32_16x16x32_bf16 v[48:51], v[184:187], v[208:211], v[48:51]
	v_mfma_f32_16x16x32_bf16 v[52:55], v[124:127], v[216:219], v[52:55]
	v_mfma_f32_16x16x32_bf16 v[56:59], v[184:187], v[216:219], v[56:59]
	s_setprio 0
	s_barrier
	s_add_i32 s70, s68, s54
	s_mov_b64 vcc, 0x180
	s_add_i32 s68, s70, 0x2000
	v_lshl_add_u64 v[142:143], v[142:143], 0, vcc
	s_mov_b32 m0, s70
	s_add_u32 s72, s50, 0x10180
	ds_read_b128 v[188:191], v137 offset:49152
	ds_read_b128 v[192:195], v137 offset:50176
	ds_read_b128 v[196:199], v137 offset:51200
	ds_read_b128 v[200:203], v137 offset:52224
	ds_read_b128 v[204:207], v137 offset:53248
	ds_read_b128 v[208:211], v137 offset:54272
	ds_read_b128 v[212:215], v137 offset:55296
	ds_read_b128 v[216:219], v137 offset:56320
	global_load_lds_dwordx4 v[142:143], off
	v_lshl_add_u64 v[142:143], v[146:147], 0, vcc
	s_mov_b32 m0, s68
	s_addc_u32 s73, s51, 0
	s_add_i32 s50, s74, s54
	global_load_lds_dwordx4 v[142:143], off
	v_lshl_add_u64 v[142:143], s[72:73], 0, v[144:145]
	s_mov_b32 m0, s50
	s_add_i32 s51, s50, 0x2000
	global_load_lds_dwordx4 v[142:143], off
	v_lshl_add_u64 v[142:143], s[72:73], 0, v[128:129]
	s_mov_b32 m0, s51
	s_nop 0
	global_load_lds_dwordx4 v[142:143], off
	v_lshl_add_u64 v[142:143], v[148:149], 0, vcc
	s_mov_b32 m0, s60
	s_nop 0
	global_load_lds_dwordx4 v[142:143], off
	v_lshl_add_u64 v[142:143], v[150:151], 0, vcc
	s_mov_b32 m0, s61
	s_nop 0
	global_load_lds_dwordx4 v[142:143], off
	s_waitcnt vmcnt(8)
	s_waitcnt lgkmcnt(0)
	s_barrier
	s_setprio 1
	s_waitcnt lgkmcnt(0)
	v_mfma_f32_16x16x32_bf16 v[0:3], v[24:27], v[212:215], v[0:3]
	v_mfma_f32_16x16x32_bf16 v[4:7], v[112:115], v[212:215], v[4:7]
	v_mfma_f32_16x16x32_bf16 v[138:141], v[24:27], v[188:191], v[138:141]
	v_mfma_f32_16x16x32_bf16 v[160:163], v[112:115], v[188:191], v[160:163]
	v_mfma_f32_16x16x32_bf16 v[164:167], v[24:27], v[196:199], v[164:167]
	v_mfma_f32_16x16x32_bf16 v[168:171], v[112:115], v[196:199], v[168:171]
	v_mfma_f32_16x16x32_bf16 v[172:175], v[24:27], v[204:207], v[172:175]
	v_mfma_f32_16x16x32_bf16 v[176:179], v[112:115], v[204:207], v[176:179]
	v_mfma_f32_16x16x32_bf16 v[0:3], v[28:31], v[216:219], v[0:3]
	v_mfma_f32_16x16x32_bf16 v[4:7], v[116:119], v[216:219], v[4:7]
	v_mfma_f32_16x16x32_bf16 v[138:141], v[28:31], v[192:195], v[138:141]
	v_mfma_f32_16x16x32_bf16 v[160:163], v[116:119], v[192:195], v[160:163]
	v_mfma_f32_16x16x32_bf16 v[164:167], v[28:31], v[200:203], v[164:167]
	v_mfma_f32_16x16x32_bf16 v[168:171], v[116:119], v[200:203], v[168:171]
	v_mfma_f32_16x16x32_bf16 v[172:175], v[28:31], v[208:211], v[172:175]
	v_mfma_f32_16x16x32_bf16 v[176:179], v[116:119], v[208:211], v[176:179]
	v_mfma_f32_16x16x32_bf16 v[8:11], v[120:123], v[188:191], v[8:11]
	v_mfma_f32_16x16x32_bf16 v[12:15], v[180:183], v[188:191], v[12:15]
	v_mfma_f32_16x16x32_bf16 v[24:27], v[120:123], v[196:199], v[60:63]
	v_mfma_f32_16x16x32_bf16 v[28:31], v[180:183], v[196:199], v[100:103]
	v_mfma_f32_16x16x32_bf16 v[60:63], v[120:123], v[204:207], v[104:107]
	v_mfma_f32_16x16x32_bf16 v[100:103], v[180:183], v[204:207], v[108:111]
	v_mfma_f32_16x16x32_bf16 v[16:19], v[120:123], v[212:215], v[16:19]
	v_mfma_f32_16x16x32_bf16 v[20:23], v[180:183], v[212:215], v[20:23]
	v_mfma_f32_16x16x32_bf16 v[8:11], v[124:127], v[192:195], v[8:11]
	v_mfma_f32_16x16x32_bf16 v[12:15], v[184:187], v[192:195], v[12:15]
	v_mfma_f32_16x16x32_bf16 v[24:27], v[124:127], v[200:203], v[24:27]
	v_mfma_f32_16x16x32_bf16 v[28:31], v[184:187], v[200:203], v[28:31]
	v_mfma_f32_16x16x32_bf16 v[60:63], v[124:127], v[208:211], v[60:63]
	v_mfma_f32_16x16x32_bf16 v[100:103], v[184:187], v[208:211], v[100:103]
	v_mfma_f32_16x16x32_bf16 v[16:19], v[124:127], v[216:219], v[16:19]
	v_mfma_f32_16x16x32_bf16 v[20:23], v[184:187], v[216:219], v[20:23]
	s_setprio 0
	s_barrier
	ds_read_b128 v[104:107], v154
	ds_read_b128 v[108:111], v154 offset:1024
	ds_read_b128 v[112:115], v154 offset:2048
	ds_read_b128 v[116:119], v154 offset:3072
	ds_read_b128 v[120:123], v155
	ds_read_b128 v[124:127], v155 offset:1024
	ds_read_b128 v[180:183], v155 offset:2048
	ds_read_b128 v[184:187], v155 offset:3072
	s_add_u32 s46, s46, 0x10180
	s_addc_u32 s47, s47, 0
	s_mov_b32 m0, s69
	v_lshl_add_u64 v[142:143], s[46:47], 0, v[132:133]
	ds_read_b128 v[188:191], v137
	ds_read_b128 v[192:195], v137 offset:1024
	ds_read_b128 v[196:199], v137 offset:2048
	ds_read_b128 v[200:203], v137 offset:3072
	ds_read_b128 v[204:207], v137 offset:4096
	ds_read_b128 v[208:211], v137 offset:5120
	ds_read_b128 v[212:215], v137 offset:6144
	ds_read_b128 v[216:219], v137 offset:7168
	global_load_lds_dwordx4 v[142:143], off
	v_lshl_add_u64 v[142:143], s[46:47], 0, v[130:131]
	s_mov_b32 m0, s5
	s_nop 0
	global_load_lds_dwordx4 v[142:143], off
	s_waitcnt vmcnt(8)
	s_waitcnt lgkmcnt(0)
	s_barrier
	s_setprio 1
	s_waitcnt lgkmcnt(0)
	v_mfma_f32_16x16x32_bf16 v[64:67], v[104:107], v[188:191], v[64:67]
	v_mfma_f32_16x16x32_bf16 v[68:71], v[112:115], v[188:191], v[68:71]
	v_mfma_f32_16x16x32_bf16 v[72:75], v[104:107], v[196:199], v[72:75]
	v_mfma_f32_16x16x32_bf16 v[76:79], v[112:115], v[196:199], v[76:79]
	v_mfma_f32_16x16x32_bf16 v[80:83], v[104:107], v[204:207], v[80:83]
	v_mfma_f32_16x16x32_bf16 v[84:87], v[112:115], v[204:207], v[84:87]
	v_mfma_f32_16x16x32_bf16 v[88:91], v[104:107], v[212:215], v[88:91]
	v_mfma_f32_16x16x32_bf16 v[92:95], v[112:115], v[212:215], v[92:95]
	v_mfma_f32_16x16x32_bf16 v[64:67], v[108:111], v[192:195], v[64:67]
	v_mfma_f32_16x16x32_bf16 v[68:71], v[116:119], v[192:195], v[68:71]
	v_mfma_f32_16x16x32_bf16 v[72:75], v[108:111], v[200:203], v[72:75]
	v_mfma_f32_16x16x32_bf16 v[76:79], v[116:119], v[200:203], v[76:79]
	v_mfma_f32_16x16x32_bf16 v[80:83], v[108:111], v[208:211], v[80:83]
	v_mfma_f32_16x16x32_bf16 v[84:87], v[116:119], v[208:211], v[84:87]
	v_mfma_f32_16x16x32_bf16 v[88:91], v[108:111], v[216:219], v[88:91]
	v_mfma_f32_16x16x32_bf16 v[92:95], v[116:119], v[216:219], v[92:95]
	v_mfma_f32_16x16x32_bf16 v[32:35], v[180:183], v[188:191], v[32:35]
	v_mfma_f32_16x16x32_bf16 v[96:99], v[120:123], v[188:191], v[96:99]
	v_mfma_f32_16x16x32_bf16 v[188:191], v[184:187], v[192:195], v[32:35]
	v_mfma_f32_16x16x32_bf16 v[32:35], v[120:123], v[196:199], v[36:39]
	v_mfma_f32_16x16x32_bf16 v[220:223], v[124:127], v[192:195], v[96:99]
	v_mfma_f32_16x16x32_bf16 v[192:195], v[124:127], v[200:203], v[32:35]
	v_mfma_f32_16x16x32_bf16 v[32:35], v[180:183], v[196:199], v[40:43]
	v_mfma_f32_16x16x32_bf16 v[40:43], v[184:187], v[200:203], v[32:35]
	v_mfma_f32_16x16x32_bf16 v[32:35], v[120:123], v[204:207], v[44:47]
	v_mfma_f32_16x16x32_bf16 v[44:47], v[124:127], v[208:211], v[32:35]
	v_mfma_f32_16x16x32_bf16 v[32:35], v[180:183], v[204:207], v[48:51]
	v_mfma_f32_16x16x32_bf16 v[48:51], v[184:187], v[208:211], v[32:35]
	v_mfma_f32_16x16x32_bf16 v[32:35], v[120:123], v[212:215], v[52:55]
	v_mfma_f32_16x16x32_bf16 v[52:55], v[124:127], v[216:219], v[32:35]
	v_mfma_f32_16x16x32_bf16 v[32:35], v[180:183], v[212:215], v[56:59]
	v_mfma_f32_16x16x32_bf16 v[56:59], v[184:187], v[216:219], v[32:35]
	s_setprio 0
	s_barrier
	s_mov_b32 m0, s65
	v_lshl_add_u64 v[142:143], s[48:49], 0, v[144:145]
	s_add_u32 s46, s48, 0x10000
	s_nop 1
	ds_read_b128 v[32:35], v137 offset:16384
	ds_read_b128 v[36:39], v137 offset:17408
	ds_read_b128 v[96:99], v137 offset:18432
	ds_read_b128 v[196:199], v137 offset:19456
	ds_read_b128 v[200:203], v137 offset:20480
	ds_read_b128 v[204:207], v137 offset:21504
	ds_read_b128 v[208:211], v137 offset:22528
	ds_read_b128 v[212:215], v137 offset:23552
	global_load_lds_dwordx4 v[142:143], off
	v_lshl_add_u64 v[250:251], s[48:49], 0, v[128:129]
	s_mov_b32 m0, s25
	s_addc_u32 s47, s49, 0
	global_load_lds_dwordx4 v[250:251], off
	v_lshl_add_u64 v[146:147], s[46:47], 0, v[144:145]
	s_mov_b32 m0, s39
	v_lshl_add_u64 v[244:245], s[52:53], 0, v[132:133]
	global_load_lds_dwordx4 v[146:147], off
	v_lshl_add_u64 v[146:147], s[46:47], 0, v[128:129]
	s_mov_b32 m0, s64
	v_lshl_add_u64 v[242:243], s[52:53], 0, v[130:131]
	global_load_lds_dwordx4 v[146:147], off
	s_mov_b32 m0, s41
	s_nop 0
	global_load_lds_dwordx4 v[244:245], off
	s_mov_b32 m0, s55
	s_nop 0
	global_load_lds_dwordx4 v[242:243], off
	s_waitcnt vmcnt(8)
	s_waitcnt lgkmcnt(0)
	s_barrier
	s_setprio 1
	s_waitcnt lgkmcnt(0)
	v_mfma_f32_16x16x32_bf16 v[0:3], v[104:107], v[208:211], v[0:3]
	v_mfma_f32_16x16x32_bf16 v[4:7], v[112:115], v[208:211], v[4:7]
	v_mfma_f32_16x16x32_bf16 v[138:141], v[104:107], v[32:35], v[138:141]
	v_mfma_f32_16x16x32_bf16 v[160:163], v[112:115], v[32:35], v[160:163]
	v_mfma_f32_16x16x32_bf16 v[164:167], v[104:107], v[96:99], v[164:167]
	v_mfma_f32_16x16x32_bf16 v[168:171], v[112:115], v[96:99], v[168:171]
	v_mfma_f32_16x16x32_bf16 v[172:175], v[104:107], v[200:203], v[172:175]
	v_mfma_f32_16x16x32_bf16 v[176:179], v[112:115], v[200:203], v[176:179]
	v_mfma_f32_16x16x32_bf16 v[0:3], v[108:111], v[212:215], v[0:3]
	v_mfma_f32_16x16x32_bf16 v[4:7], v[116:119], v[212:215], v[4:7]
	v_mfma_f32_16x16x32_bf16 v[138:141], v[108:111], v[36:39], v[138:141]
	v_mfma_f32_16x16x32_bf16 v[160:163], v[116:119], v[36:39], v[160:163]
	v_mfma_f32_16x16x32_bf16 v[164:167], v[108:111], v[196:199], v[164:167]
	v_mfma_f32_16x16x32_bf16 v[168:171], v[116:119], v[196:199], v[168:171]
	v_mfma_f32_16x16x32_bf16 v[172:175], v[108:111], v[204:207], v[172:175]
	v_mfma_f32_16x16x32_bf16 v[176:179], v[116:119], v[204:207], v[176:179]
	v_mfma_f32_16x16x32_bf16 v[8:11], v[120:123], v[32:35], v[8:11]
	v_mfma_f32_16x16x32_bf16 v[12:15], v[180:183], v[32:35], v[12:15]
	v_mfma_f32_16x16x32_bf16 v[24:27], v[120:123], v[96:99], v[24:27]
	v_mfma_f32_16x16x32_bf16 v[28:31], v[180:183], v[96:99], v[28:31]
	v_mfma_f32_16x16x32_bf16 v[32:35], v[120:123], v[200:203], v[60:63]
	v_mfma_f32_16x16x32_bf16 v[24:27], v[124:127], v[196:199], v[24:27]
	v_mfma_f32_16x16x32_bf16 v[28:31], v[184:187], v[196:199], v[28:31]
	v_mfma_f32_16x16x32_bf16 v[196:199], v[124:127], v[204:207], v[32:35]
	v_mfma_f32_16x16x32_bf16 v[32:35], v[180:183], v[200:203], v[100:103]
	v_mfma_f32_16x16x32_bf16 v[16:19], v[120:123], v[208:211], v[16:19]
	v_mfma_f32_16x16x32_bf16 v[8:11], v[124:127], v[36:39], v[8:11]
	v_mfma_f32_16x16x32_bf16 v[12:15], v[184:187], v[36:39], v[12:15]
	v_mfma_f32_16x16x32_bf16 v[200:203], v[184:187], v[204:207], v[32:35]
	v_mfma_f32_16x16x32_bf16 v[204:207], v[124:127], v[212:215], v[16:19]
	v_mfma_f32_16x16x32_bf16 v[16:19], v[180:183], v[208:211], v[20:23]
	v_mfma_f32_16x16x32_bf16 v[180:183], v[184:187], v[212:215], v[16:19]
	s_setprio 0
	s_barrier
	ds_read_b128 v[60:63], v156
	ds_read_b128 v[184:187], v156 offset:1024
	ds_read_b128 v[208:211], v156 offset:2048
	ds_read_b128 v[212:215], v156 offset:3072
	ds_read_b128 v[216:219], v157
	ds_read_b128 v[224:227], v157 offset:1024
	ds_read_b128 v[228:231], v157 offset:2048
	ds_read_b128 v[232:235], v157 offset:3072
	s_add_u32 s46, s52, 0x10000
	s_addc_u32 s47, s53, 0
	s_mov_b32 m0, s56
	v_lshl_add_u64 v[32:33], s[46:47], 0, v[132:133]
	ds_read_b128 v[16:19], v137 offset:32768
	ds_read_b128 v[20:23], v137 offset:33792
	ds_read_b128 v[108:111], v137 offset:34816
	ds_read_b128 v[236:239], v137 offset:35840
	ds_read_b128 v[246:249], v137 offset:36864
	ds_read_b128 v[146:149], v137 offset:37888
	ds_read_b128 v[150:153], v137 offset:38912
	ds_read_b128 v[154:157], v137 offset:39936
	global_load_lds_dwordx4 v[32:33], off
	v_lshl_add_u64 v[32:33], s[46:47], 0, v[130:131]
	s_mov_b32 m0, s57
	s_nop 0
	global_load_lds_dwordx4 v[32:33], off
	s_waitcnt vmcnt(8)
	s_waitcnt lgkmcnt(0)
	s_barrier
	s_setprio 1
	s_waitcnt lgkmcnt(0)
	v_mfma_f32_16x16x32_bf16 v[32:35], v[60:63], v[16:19], v[64:67]
	v_mfma_f32_16x16x32_bf16 v[112:115], v[184:187], v[20:23], v[32:35]
	v_mfma_f32_16x16x32_bf16 v[32:35], v[208:211], v[16:19], v[68:71]
	v_mfma_f32_16x16x32_bf16 v[116:119], v[212:215], v[20:23], v[32:35]
	v_mfma_f32_16x16x32_bf16 v[32:35], v[60:63], v[108:111], v[72:75]
	v_mfma_f32_16x16x32_bf16 v[96:99], v[184:187], v[236:239], v[32:35]
	v_mfma_f32_16x16x32_bf16 v[32:35], v[208:211], v[108:111], v[76:79]
	v_mfma_f32_16x16x32_bf16 v[100:103], v[212:215], v[236:239], v[32:35]
	v_mfma_f32_16x16x32_bf16 v[32:35], v[60:63], v[246:249], v[80:83]
	v_mfma_f32_16x16x32_bf16 v[64:67], v[184:187], v[146:149], v[32:35]
	v_mfma_f32_16x16x32_bf16 v[32:35], v[208:211], v[246:249], v[84:87]
	v_mfma_f32_16x16x32_bf16 v[68:71], v[212:215], v[146:149], v[32:35]
	v_mfma_f32_16x16x32_bf16 v[32:35], v[60:63], v[150:153], v[88:91]
	v_mfma_f32_16x16x32_bf16 v[36:39], v[208:211], v[150:153], v[92:95]
	v_mfma_f32_16x16x32_bf16 v[32:35], v[184:187], v[154:157], v[32:35]
	v_mfma_f32_16x16x32_bf16 v[36:39], v[212:215], v[154:157], v[36:39]
	v_mfma_f32_16x16x32_bf16 v[72:75], v[216:219], v[16:19], v[220:223]
	v_mfma_f32_16x16x32_bf16 v[16:19], v[228:231], v[16:19], v[188:191]
	v_mfma_f32_16x16x32_bf16 v[124:127], v[232:235], v[20:23], v[16:19]
	v_mfma_f32_16x16x32_bf16 v[16:19], v[216:219], v[108:111], v[192:195]
	v_mfma_f32_16x16x32_bf16 v[104:107], v[224:227], v[236:239], v[16:19]
	v_mfma_f32_16x16x32_bf16 v[16:19], v[228:231], v[108:111], v[40:43]
	v_mfma_f32_16x16x32_bf16 v[108:111], v[232:235], v[236:239], v[16:19]
	v_mfma_f32_16x16x32_bf16 v[16:19], v[216:219], v[246:249], v[44:47]
	v_mfma_f32_16x16x32_bf16 v[120:123], v[224:227], v[20:23], v[72:75]
	v_mfma_f32_16x16x32_bf16 v[72:75], v[224:227], v[146:149], v[16:19]
	v_mfma_f32_16x16x32_bf16 v[16:19], v[228:231], v[246:249], v[48:51]
	v_mfma_f32_16x16x32_bf16 v[76:79], v[232:235], v[146:149], v[16:19]
	v_mfma_f32_16x16x32_bf16 v[16:19], v[216:219], v[150:153], v[52:55]
	v_mfma_f32_16x16x32_bf16 v[40:43], v[224:227], v[154:157], v[16:19]
	v_mfma_f32_16x16x32_bf16 v[16:19], v[228:231], v[150:153], v[56:59]
	v_mfma_f32_16x16x32_bf16 v[44:47], v[232:235], v[154:157], v[16:19]
	s_setprio 0
	s_barrier
	s_mov_b32 m0, s70
	s_nop 3
	v_lshl_add_u64 v[16:17], v[142:143], 0, s[20:21]
	s_add_u32 s46, s48, 0x10080
	ds_read_b128 v[56:59], v137 offset:49152
	ds_read_b128 v[92:95], v137 offset:50176
	ds_read_b128 v[146:149], v137 offset:51200
	ds_read_b128 v[150:153], v137 offset:52224
	ds_read_b128 v[154:157], v137 offset:53248
	ds_read_b128 v[188:191], v137 offset:54272
	ds_read_b128 v[192:195], v137 offset:55296
	ds_read_b128 v[220:223], v137 offset:56320
	global_load_lds_dwordx4 v[16:17], off
	v_lshl_add_u64 v[16:17], v[250:251], 0, s[20:21]
	s_mov_b32 m0, s68
	s_addc_u32 s47, s49, 0
	global_load_lds_dwordx4 v[16:17], off
	v_lshl_add_u64 v[16:17], s[46:47], 0, v[144:145]
	s_mov_b32 m0, s50
	s_nop 0
	global_load_lds_dwordx4 v[16:17], off
	v_lshl_add_u64 v[16:17], s[46:47], 0, v[128:129]
	s_mov_b32 m0, s51
	s_nop 0
	global_load_lds_dwordx4 v[16:17], off
	v_lshl_add_u64 v[16:17], v[244:245], 0, s[20:21]
	s_mov_b32 m0, s60
	s_nop 0
	global_load_lds_dwordx4 v[16:17], off
	v_lshl_add_u64 v[16:17], v[242:243], 0, s[20:21]
	s_mov_b32 m0, s61
	s_nop 0
	global_load_lds_dwordx4 v[16:17], off
	s_waitcnt vmcnt(8)
	s_waitcnt lgkmcnt(0)
	s_barrier
	s_setprio 1
	s_waitcnt lgkmcnt(0)
	v_mfma_f32_16x16x32_bf16 v[16:19], v[60:63], v[56:59], v[138:141]
	v_mfma_f32_16x16x32_bf16 v[80:83], v[184:187], v[92:95], v[16:19]
	v_mfma_f32_16x16x32_bf16 v[16:19], v[208:211], v[56:59], v[160:163]
	v_mfma_f32_16x16x32_bf16 v[84:87], v[212:215], v[92:95], v[16:19]
	v_mfma_f32_16x16x32_bf16 v[16:19], v[60:63], v[146:149], v[164:167]
	v_mfma_f32_16x16x32_bf16 v[48:51], v[184:187], v[150:153], v[16:19]
	v_mfma_f32_16x16x32_bf16 v[16:19], v[208:211], v[146:149], v[168:171]
	v_mfma_f32_16x16x32_bf16 v[52:55], v[212:215], v[150:153], v[16:19]
	v_mfma_f32_16x16x32_bf16 v[16:19], v[60:63], v[154:157], v[172:175]
	v_mfma_f32_16x16x32_bf16 v[20:23], v[208:211], v[154:157], v[176:179]
	v_mfma_f32_16x16x32_bf16 v[0:3], v[60:63], v[192:195], v[0:3]
	v_mfma_f32_16x16x32_bf16 v[4:7], v[208:211], v[192:195], v[4:7]
	v_mfma_f32_16x16x32_bf16 v[16:19], v[184:187], v[188:191], v[16:19]
	v_mfma_f32_16x16x32_bf16 v[20:23], v[212:215], v[188:191], v[20:23]
	v_mfma_f32_16x16x32_bf16 v[0:3], v[184:187], v[220:223], v[0:3]
	v_mfma_f32_16x16x32_bf16 v[4:7], v[212:215], v[220:223], v[4:7]
	v_mfma_f32_16x16x32_bf16 v[8:11], v[216:219], v[56:59], v[8:11]
	v_mfma_f32_16x16x32_bf16 v[88:91], v[224:227], v[92:95], v[8:11]
	v_mfma_f32_16x16x32_bf16 v[8:11], v[228:231], v[56:59], v[12:15]
	v_mfma_f32_16x16x32_bf16 v[92:95], v[232:235], v[92:95], v[8:11]
	v_mfma_f32_16x16x32_bf16 v[8:11], v[216:219], v[146:149], v[24:27]
	v_mfma_f32_16x16x32_bf16 v[56:59], v[224:227], v[150:153], v[8:11]
	v_mfma_f32_16x16x32_bf16 v[8:11], v[228:231], v[146:149], v[28:31]
	v_mfma_f32_16x16x32_bf16 v[60:63], v[232:235], v[150:153], v[8:11]
	v_mfma_f32_16x16x32_bf16 v[8:11], v[216:219], v[154:157], v[196:199]
	v_mfma_f32_16x16x32_bf16 v[24:27], v[224:227], v[188:191], v[8:11]
	v_mfma_f32_16x16x32_bf16 v[8:11], v[228:231], v[154:157], v[200:203]
	v_mfma_f32_16x16x32_bf16 v[28:31], v[232:235], v[188:191], v[8:11]
	v_mfma_f32_16x16x32_bf16 v[8:11], v[216:219], v[192:195], v[204:207]
	v_mfma_f32_16x16x32_bf16 v[12:15], v[228:231], v[192:195], v[180:183]
	v_mfma_f32_16x16x32_bf16 v[8:11], v[224:227], v[220:223], v[8:11]
	v_mfma_f32_16x16x32_bf16 v[12:15], v[232:235], v[220:223], v[12:15]
	s_setprio 0
	s_barrier
	s_andn2_b64 vcc, exec, s[12:13]
	s_cbranch_vccnz .LBB0_739
	s_barrier
